# v8 + in the 6-DMA load segments the LDS-DMA loads are issued before the ds_read_b128 fragment reads (was reads first)
# baseline (speedup 1.0000x reference)
; #define PG8_STAGE(bufoff, gbase, voff) do { _Pragma("unroll") for (int _i = 0; _i < 2; ++_i) \
;         __builtin_amdgcn_global_load_lds((const unsigned*)((const char*)(gbase) + (voff)[_i]), (LAS unsigned*)(lds + (bufoff) + ldsw + _i * 8192), 16, 0, 0); } while (0)
; #define PG8_LDA(dst, b, h) do { _Pragma("unroll") for (int m = 0; m < 4; ++m) _Pragma("unroll") for (int k = 0; k < 2; ++k) dst[m][k] = *(const LAS bf16x8*)(lds + PG8_SA(b, h) + aoff + m * 2048 + k * KOFF); } while (0)
; #define PG8_LDB(dst, b, h) do { _Pragma("unroll") for (int n = 0; n < 2; ++n) _Pragma("unroll") for (int k = 0; k < 2; ++k) dst[n][k] = *(const LAS bf16x8*)(lds + PG8_SB(b, h) + boff + n * 2048 + k * KOFF); } while (0)
; #define PG8_WAIT_V(n) asm volatile("s_waitcnt vmcnt(" #n ")" ::: "memory")
; #define PG8_WAIT_L(n) asm volatile("s_waitcnt lgkmcnt(" #n ")" ::: "memory")
; #define PG8_BAR __builtin_amdgcn_s_barrier()
; #define PG8_SCHED __builtin_amdgcn_sched_barrier(0)
; template <class Epi, bool ALIGN_EPI = true, bool FP8 = false>
; __device__ __forceinline__ void gemm_phase(LAS unsigned char* lds, const Gemm g, const StaticOrder& S, const Epi& E, const int wid) {
;     ...
;             const char* a1 = cA + (size_t)(t + 1) * kstep;
;             const char* a2 = last ? nA : cA + (size_t)(t + 2) * kstep; const char* b2 = last ? nB : cB + (size_t)(t + 2) * kstep;
;             const char* a3 = a2 + kstep; const char* b3 = b2 + kstep;
;             PG8_LDB(B0, 0, 0); PG8_LDB(B1, 0, 1); PG8_SCHED; PG8_LDA(At, 0, 0); PG8_STAGE(PG8_SA(1, 1), a1 + hstep, voffA);
;             PG8_WAIT_V(8); PG8_WAIT_L(0); PG8_BAR; PG8_MMA(0, 0, At, B0); PG8_MMA(0, 1, At, B1); PG8_BAR; PG8_SCHED;
;             PG8_LDA(At, 0, 1); PG8_STAGE(PG8_SB(0, 0), b2, voffB); PG8_STAGE(PG8_SB(0, 1), b2 + hstep, voffB); PG8_STAGE(PG8_SA(0, 0), a2, voffA);
;             PG8_WAIT_V(8); PG8_WAIT_L(0); PG8_BAR; PG8_MMA(1, 0, At, B0); PG8_MMA(1, 1, At, B1); PG8_BAR; PG8_SCHED;
.LBB0_506:
	ds_read_b128 v[146:149], v137
	ds_read_b128 v[154:157], v137 offset:1024
	ds_read_b128 v[158:161], v137 offset:2048
	ds_read_b128 v[162:165], v137 offset:3072
	ds_read_b128 v[166:169], v152
	ds_read_b128 v[170:173], v152 offset:1024
	ds_read_b128 v[174:177], v152 offset:2048
	ds_read_b128 v[178:181], v152 offset:3072
	s_add_i32 s52, s34, 2
	s_add_u32 s35, s30, 0xfff80080
	s_addc_u32 s36, s31, -1
	s_cmp_eq_u32 s39, s34
	s_cselect_b32 s34, s38, s42
	s_cselect_b32 s37, s3, s36
	s_cselect_b32 s36, s23, s35
	s_cselect_b32 s35, s25, s43
	v_lshl_add_u64 v[214:215], s[30:31], 0, v[140:141]
	s_add_i32 m0, s75, 0xc000
	ds_read_b128 v[182:185], v153
	ds_read_b128 v[186:189], v153 offset:1024
	ds_read_b128 v[190:193], v153 offset:2048
	ds_read_b128 v[194:197], v153 offset:3072
	ds_read_b128 v[198:201], v153 offset:4096
	ds_read_b128 v[202:205], v153 offset:5120
	ds_read_b128 v[206:209], v153 offset:6144
	ds_read_b128 v[210:213], v153 offset:7168
	global_load_lds_dwordx4 v[214:215], off
	v_lshl_add_u64 v[214:215], s[30:31], 0, v[142:143]
	s_add_i32 m0, s75, 0xe000
	s_nop 0
	global_load_lds_dwordx4 v[214:215], off
	s_setprio 1
	s_waitcnt vmcnt(8) lgkmcnt(0)
	s_barrier
	v_mfma_f32_16x16x32_bf16 v[124:127], v[146:149], v[182:185], v[124:127]
	v_mfma_f32_16x16x32_bf16 v[120:123], v[158:161], v[182:185], v[120:123]
	v_mfma_f32_16x16x32_bf16 v[108:111], v[146:149], v[190:193], v[108:111]
	v_mfma_f32_16x16x32_bf16 v[104:107], v[158:161], v[190:193], v[104:107]
	v_mfma_f32_16x16x32_bf16 v[92:95], v[146:149], v[198:201], v[92:95]
	v_mfma_f32_16x16x32_bf16 v[88:91], v[158:161], v[198:201], v[88:91]
	v_mfma_f32_16x16x32_bf16 v[76:79], v[146:149], v[206:209], v[76:79]
	v_mfma_f32_16x16x32_bf16 v[72:75], v[158:161], v[206:209], v[72:75]
	v_mfma_f32_16x16x32_bf16 v[124:127], v[154:157], v[186:189], v[124:127]
	v_mfma_f32_16x16x32_bf16 v[120:123], v[162:165], v[186:189], v[120:123]
	v_mfma_f32_16x16x32_bf16 v[108:111], v[154:157], v[194:197], v[108:111]
	v_mfma_f32_16x16x32_bf16 v[104:107], v[162:165], v[194:197], v[104:107]
	v_mfma_f32_16x16x32_bf16 v[92:95], v[154:157], v[202:205], v[92:95]
	v_mfma_f32_16x16x32_bf16 v[88:91], v[162:165], v[202:205], v[88:91]
	v_mfma_f32_16x16x32_bf16 v[76:79], v[154:157], v[210:213], v[76:79]
	v_mfma_f32_16x16x32_bf16 v[72:75], v[162:165], v[210:213], v[72:75]
	v_mfma_f32_16x16x32_bf16 v[116:119], v[166:169], v[182:185], v[116:119]
	v_mfma_f32_16x16x32_bf16 v[112:115], v[174:177], v[182:185], v[112:115]
	v_mfma_f32_16x16x32_bf16 v[100:103], v[166:169], v[190:193], v[100:103]
	v_mfma_f32_16x16x32_bf16 v[96:99], v[174:177], v[190:193], v[96:99]
	v_mfma_f32_16x16x32_bf16 v[84:87], v[166:169], v[198:201], v[84:87]
	v_mfma_f32_16x16x32_bf16 v[80:83], v[174:177], v[198:201], v[80:83]
	v_mfma_f32_16x16x32_bf16 v[68:71], v[166:169], v[206:209], v[68:71]
	v_mfma_f32_16x16x32_bf16 v[64:67], v[174:177], v[206:209], v[64:67]
	v_mfma_f32_16x16x32_bf16 v[116:119], v[170:173], v[186:189], v[116:119]
	v_mfma_f32_16x16x32_bf16 v[112:115], v[178:181], v[186:189], v[112:115]
	v_mfma_f32_16x16x32_bf16 v[100:103], v[170:173], v[194:197], v[100:103]
	v_mfma_f32_16x16x32_bf16 v[96:99], v[178:181], v[194:197], v[96:99]
	v_mfma_f32_16x16x32_bf16 v[84:87], v[170:173], v[202:205], v[84:87]
	v_mfma_f32_16x16x32_bf16 v[80:83], v[178:181], v[202:205], v[80:83]
	v_mfma_f32_16x16x32_bf16 v[68:71], v[170:173], v[210:213], v[68:71]
	v_mfma_f32_16x16x32_bf16 v[64:67], v[178:181], v[210:213], v[64:67]
	s_barrier
	s_setprio 0
	s_add_i32 s54, s86, s48
	v_lshl_add_u64 v[214:215], s[34:35], 0, v[132:133]
	s_mov_b32 m0, s54
	s_nop 0
	global_load_lds_dwordx4 v[214:215], off
	s_add_i32 m0, s54, 0x2000
	s_add_u32 s64, s34, 0x80000
	v_lshl_add_u64 v[216:217], s[34:35], 0, v[128:129]
	s_addc_u32 s65, s35, 0
	s_add_i32 s54, s87, s48
	global_load_lds_dwordx4 v[216:217], off
	v_lshl_add_u64 v[218:219], s[64:65], 0, v[132:133]
	s_mov_b32 m0, s54
	v_lshl_add_u64 v[220:221], s[36:37], 0, v[130:131]
	global_load_lds_dwordx4 v[218:219], off
	v_lshl_add_u64 v[218:219], s[64:65], 0, v[128:129]
	s_add_i32 m0, s54, 0x2000
	s_nop 0
	global_load_lds_dwordx4 v[218:219], off
	v_lshl_add_u64 v[218:219], s[36:37], 0, v[134:135]
	s_mov_b32 m0, s75
	s_nop 0
	global_load_lds_dwordx4 v[218:219], off
	s_mov_b32 m0, s76
	s_nop 0
	global_load_lds_dwordx4 v[220:221], off
	ds_read_b128 v[182:185], v153 offset:16384
	ds_read_b128 v[186:189], v153 offset:17408
	ds_read_b128 v[190:193], v153 offset:18432
	ds_read_b128 v[194:197], v153 offset:19456
	ds_read_b128 v[198:201], v153 offset:20480
	ds_read_b128 v[202:205], v153 offset:21504
	ds_read_b128 v[206:209], v153 offset:22528
	ds_read_b128 v[210:213], v153 offset:23552
	s_setprio 1
	s_waitcnt vmcnt(8) lgkmcnt(0)
	s_barrier
; #define PG8_STAGE(bufoff, gbase, voff) do { _Pragma("unroll") for (int _i = 0; _i < 2; ++_i) \
;         __builtin_amdgcn_global_load_lds((const unsigned*)((const char*)(gbase) + (voff)[_i]), (LAS unsigned*)(lds + (bufoff) + ldsw + _i * 8192), 16, 0, 0); } while (0)
; #define PG8_LDA(dst, b, h) do { _Pragma("unroll") for (int m = 0; m < 4; ++m) _Pragma("unroll") for (int k = 0; k < 2; ++k) dst[m][k] = *(const LAS bf16x8*)(lds + PG8_SA(b, h) + aoff + m * 2048 + k * KOFF); } while (0)
; #define PG8_LDB(dst, b, h) do { _Pragma("unroll") for (int n = 0; n < 2; ++n) _Pragma("unroll") for (int k = 0; k < 2; ++k) dst[n][k] = *(const LAS bf16x8*)(lds + PG8_SB(b, h) + boff + n * 2048 + k * KOFF); } while (0)
; #define PG8_WAIT_V(n) asm volatile("s_waitcnt vmcnt(" #n ")" ::: "memory")
; #define PG8_WAIT_L(n) asm volatile("s_waitcnt lgkmcnt(" #n ")" ::: "memory")
; #define PG8_BAR __builtin_amdgcn_s_barrier()
; #define PG8_SCHED __builtin_amdgcn_sched_barrier(0)
; template <class Epi, bool ALIGN_EPI = true, bool FP8 = false>
; __device__ __forceinline__ void gemm_phase(LAS unsigned char* lds, const Gemm g, const StaticOrder& S, const Epi& E, const int wid) {
;     ...
;             PG8_WAIT_V(8); PG8_WAIT_L(0); PG8_BAR; PG8_MMA(1, 0, At, B0); PG8_MMA(1, 1, At, B1); PG8_BAR; PG8_SCHED;
;             PG8_LDB(B0, 1, 0); PG8_LDB(B1, 1, 1); PG8_SCHED; PG8_LDA(At, 1, 0); PG8_STAGE(PG8_SA(0, 1), a2 + hstep, voffA);
;             PG8_WAIT_V(8); PG8_WAIT_L(0); PG8_BAR; PG8_MMA(0, 0, At, B0); PG8_MMA(0, 1, At, B1); PG8_BAR; PG8_SCHED;
	v_mfma_f32_16x16x32_bf16 v[60:63], v[146:149], v[182:185], v[60:63]
	v_mfma_f32_16x16x32_bf16 v[56:59], v[158:161], v[182:185], v[56:59]
	v_mfma_f32_16x16x32_bf16 v[44:47], v[146:149], v[190:193], v[44:47]
	v_mfma_f32_16x16x32_bf16 v[40:43], v[158:161], v[190:193], v[40:43]
	v_mfma_f32_16x16x32_bf16 v[28:31], v[146:149], v[198:201], v[28:31]
	v_mfma_f32_16x16x32_bf16 v[24:27], v[158:161], v[198:201], v[24:27]
	v_mfma_f32_16x16x32_bf16 v[12:15], v[146:149], v[206:209], v[12:15]
	v_mfma_f32_16x16x32_bf16 v[8:11], v[158:161], v[206:209], v[8:11]
	v_mfma_f32_16x16x32_bf16 v[60:63], v[154:157], v[186:189], v[60:63]
	v_mfma_f32_16x16x32_bf16 v[56:59], v[162:165], v[186:189], v[56:59]
	v_mfma_f32_16x16x32_bf16 v[44:47], v[154:157], v[194:197], v[44:47]
	v_mfma_f32_16x16x32_bf16 v[40:43], v[162:165], v[194:197], v[40:43]
	v_mfma_f32_16x16x32_bf16 v[28:31], v[154:157], v[202:205], v[28:31]
	v_mfma_f32_16x16x32_bf16 v[24:27], v[162:165], v[202:205], v[24:27]
	v_mfma_f32_16x16x32_bf16 v[12:15], v[154:157], v[210:213], v[12:15]
	v_mfma_f32_16x16x32_bf16 v[8:11], v[162:165], v[210:213], v[8:11]
	v_mfma_f32_16x16x32_bf16 v[52:55], v[166:169], v[182:185], v[52:55]
	v_mfma_f32_16x16x32_bf16 v[48:51], v[174:177], v[182:185], v[48:51]
	v_mfma_f32_16x16x32_bf16 v[36:39], v[166:169], v[190:193], v[36:39]
	v_mfma_f32_16x16x32_bf16 v[32:35], v[174:177], v[190:193], v[32:35]
	v_mfma_f32_16x16x32_bf16 v[20:23], v[166:169], v[198:201], v[20:23]
	v_mfma_f32_16x16x32_bf16 v[16:19], v[174:177], v[198:201], v[16:19]
	v_mfma_f32_16x16x32_bf16 v[4:7], v[166:169], v[206:209], v[4:7]
	v_mfma_f32_16x16x32_bf16 v[0:3], v[174:177], v[206:209], v[0:3]
	v_mfma_f32_16x16x32_bf16 v[52:55], v[170:173], v[186:189], v[52:55]
	v_mfma_f32_16x16x32_bf16 v[48:51], v[178:181], v[186:189], v[48:51]
	v_mfma_f32_16x16x32_bf16 v[36:39], v[170:173], v[194:197], v[36:39]
	v_mfma_f32_16x16x32_bf16 v[32:35], v[178:181], v[194:197], v[32:35]
	v_mfma_f32_16x16x32_bf16 v[20:23], v[170:173], v[202:205], v[20:23]
	v_mfma_f32_16x16x32_bf16 v[16:19], v[178:181], v[202:205], v[16:19]
	v_mfma_f32_16x16x32_bf16 v[4:7], v[170:173], v[210:213], v[4:7]
	v_mfma_f32_16x16x32_bf16 v[0:3], v[178:181], v[210:213], v[0:3]
	s_barrier
	s_setprio 0
	s_add_i32 s54, 0, 0x18000
	s_add_i32 s64, 0, 0x1c000
	v_add_u32_e32 v162, s54, v150
	v_add_u32_e32 v178, s64, v150
	ds_read_b128 v[146:149], v162
	ds_read_b128 v[154:157], v162 offset:1024
	ds_read_b128 v[158:161], v162 offset:2048
	ds_read_b128 v[162:165], v162 offset:3072
	ds_read_b128 v[166:169], v178
	ds_read_b128 v[170:173], v178 offset:1024
	ds_read_b128 v[174:177], v178 offset:2048
	ds_read_b128 v[178:181], v178 offset:3072
	s_add_u32 s36, s36, 0x80000
	s_addc_u32 s37, s37, 0
	s_mov_b32 m0, s77
	v_lshl_add_u64 v[222:223], s[36:37], 0, v[134:135]
	ds_read_b128 v[182:185], v153 offset:32768
	ds_read_b128 v[186:189], v153 offset:33792
	ds_read_b128 v[190:193], v153 offset:34816
	ds_read_b128 v[194:197], v153 offset:35840
	ds_read_b128 v[198:201], v153 offset:36864
	ds_read_b128 v[202:205], v153 offset:37888
	ds_read_b128 v[206:209], v153 offset:38912
	ds_read_b128 v[210:213], v153 offset:39936
	global_load_lds_dwordx4 v[222:223], off
	v_lshl_add_u64 v[222:223], s[36:37], 0, v[130:131]
	s_mov_b32 m0, s78
	s_nop 0
	global_load_lds_dwordx4 v[222:223], off
	s_setprio 1
	s_waitcnt vmcnt(8) lgkmcnt(0)
	s_barrier
	v_mfma_f32_16x16x32_bf16 v[124:127], v[146:149], v[182:185], v[124:127]
	v_mfma_f32_16x16x32_bf16 v[120:123], v[158:161], v[182:185], v[120:123]
	v_mfma_f32_16x16x32_bf16 v[108:111], v[146:149], v[190:193], v[108:111]
	v_mfma_f32_16x16x32_bf16 v[104:107], v[158:161], v[190:193], v[104:107]
	v_mfma_f32_16x16x32_bf16 v[92:95], v[146:149], v[198:201], v[92:95]
	v_mfma_f32_16x16x32_bf16 v[88:91], v[158:161], v[198:201], v[88:91]
	v_mfma_f32_16x16x32_bf16 v[76:79], v[146:149], v[206:209], v[76:79]
	v_mfma_f32_16x16x32_bf16 v[72:75], v[158:161], v[206:209], v[72:75]
	v_mfma_f32_16x16x32_bf16 v[124:127], v[154:157], v[186:189], v[124:127]
	v_mfma_f32_16x16x32_bf16 v[120:123], v[162:165], v[186:189], v[120:123]
	v_mfma_f32_16x16x32_bf16 v[108:111], v[154:157], v[194:197], v[108:111]
	v_mfma_f32_16x16x32_bf16 v[104:107], v[162:165], v[194:197], v[104:107]
	v_mfma_f32_16x16x32_bf16 v[92:95], v[154:157], v[202:205], v[92:95]
	v_mfma_f32_16x16x32_bf16 v[88:91], v[162:165], v[202:205], v[88:91]
	v_mfma_f32_16x16x32_bf16 v[76:79], v[154:157], v[210:213], v[76:79]
	v_mfma_f32_16x16x32_bf16 v[72:75], v[162:165], v[210:213], v[72:75]
	v_mfma_f32_16x16x32_bf16 v[116:119], v[166:169], v[182:185], v[116:119]
	v_mfma_f32_16x16x32_bf16 v[112:115], v[174:177], v[182:185], v[112:115]
	v_mfma_f32_16x16x32_bf16 v[100:103], v[166:169], v[190:193], v[100:103]
	v_mfma_f32_16x16x32_bf16 v[96:99], v[174:177], v[190:193], v[96:99]
	v_mfma_f32_16x16x32_bf16 v[84:87], v[166:169], v[198:201], v[84:87]
	v_mfma_f32_16x16x32_bf16 v[80:83], v[174:177], v[198:201], v[80:83]
	v_mfma_f32_16x16x32_bf16 v[68:71], v[166:169], v[206:209], v[68:71]
	v_mfma_f32_16x16x32_bf16 v[64:67], v[174:177], v[206:209], v[64:67]
	v_mfma_f32_16x16x32_bf16 v[116:119], v[170:173], v[186:189], v[116:119]
	v_mfma_f32_16x16x32_bf16 v[112:115], v[178:181], v[186:189], v[112:115]
	v_mfma_f32_16x16x32_bf16 v[100:103], v[170:173], v[194:197], v[100:103]
	v_mfma_f32_16x16x32_bf16 v[96:99], v[178:181], v[194:197], v[96:99]
	v_mfma_f32_16x16x32_bf16 v[84:87], v[170:173], v[202:205], v[84:87]
	v_mfma_f32_16x16x32_bf16 v[80:83], v[178:181], v[202:205], v[80:83]
	v_mfma_f32_16x16x32_bf16 v[68:71], v[170:173], v[210:213], v[68:71]
	v_mfma_f32_16x16x32_bf16 v[64:67], v[178:181], v[210:213], v[64:67]
	s_barrier
; #define PG8_STAGE(bufoff, gbase, voff) do { _Pragma("unroll") for (int _i = 0; _i < 2; ++_i) \
;         __builtin_amdgcn_global_load_lds((const unsigned*)((const char*)(gbase) + (voff)[_i]), (LAS unsigned*)(lds + (bufoff) + ldsw + _i * 8192), 16, 0, 0); } while (0)
; #define PG8_LDA(dst, b, h) do { _Pragma("unroll") for (int m = 0; m < 4; ++m) _Pragma("unroll") for (int k = 0; k < 2; ++k) dst[m][k] = *(const LAS bf16x8*)(lds + PG8_SA(b, h) + aoff + m * 2048 + k * KOFF); } while (0)
; #define PG8_WAIT_V(n) asm volatile("s_waitcnt vmcnt(" #n ")" ::: "memory")
; #define PG8_WAIT_L(n) asm volatile("s_waitcnt lgkmcnt(" #n ")" ::: "memory")
; #define PG8_BAR __builtin_amdgcn_s_barrier()
; #define PG8_SCHED __builtin_amdgcn_sched_barrier(0)
; template <class Epi, bool ALIGN_EPI = true, bool FP8 = false>
; __device__ __forceinline__ void gemm_phase(LAS unsigned char* lds, const Gemm g, const StaticOrder& S, const Epi& E, const int wid) {
;     ...
;             PG8_LDA(At, 1, 1); PG8_STAGE(PG8_SB(1, 0), b3, voffB); PG8_STAGE(PG8_SB(1, 1), b3 + hstep, voffB); PG8_STAGE(PG8_SA(1, 0), a3, voffA);
;             PG8_WAIT_V(8); PG8_WAIT_L(0); PG8_BAR; PG8_MMA(1, 0, At, B0); PG8_MMA(1, 1, At, B1); PG8_BAR; PG8_SCHED;
;         }
	s_setprio 0
	s_add_i32 s36, s54, s48
	v_lshl_add_u64 v[214:215], v[214:215], 0, s[16:17]
	s_mov_b32 m0, s36
	s_nop 0
	global_load_lds_dwordx4 v[214:215], off
	s_add_i32 m0, s36, 0x2000
	s_add_u32 s34, s34, 0x80080
	v_lshl_add_u64 v[214:215], v[216:217], 0, s[16:17]
	s_addc_u32 s35, s35, 0
	s_add_i32 s36, s64, s48
	global_load_lds_dwordx4 v[214:215], off
	v_lshl_add_u64 v[214:215], s[34:35], 0, v[132:133]
	s_mov_b32 m0, s36
	s_nop 0
	global_load_lds_dwordx4 v[214:215], off
	v_lshl_add_u64 v[214:215], s[34:35], 0, v[128:129]
	s_add_i32 m0, s36, 0x2000
	s_nop 0
	global_load_lds_dwordx4 v[214:215], off
	v_lshl_add_u64 v[214:215], v[218:219], 0, s[16:17]
	s_mov_b32 m0, s83
	s_nop 0
	global_load_lds_dwordx4 v[214:215], off
	v_lshl_add_u64 v[214:215], v[220:221], 0, s[16:17]
	s_mov_b32 m0, s84
	s_nop 0
	global_load_lds_dwordx4 v[214:215], off
	ds_read_b128 v[182:185], v153 offset:49152
	ds_read_b128 v[186:189], v153 offset:50176
	ds_read_b128 v[190:193], v153 offset:51200
	ds_read_b128 v[194:197], v153 offset:52224
	ds_read_b128 v[198:201], v153 offset:53248
	ds_read_b128 v[202:205], v153 offset:54272
	ds_read_b128 v[206:209], v153 offset:55296
	ds_read_b128 v[210:213], v153 offset:56320
	s_setprio 1
	s_waitcnt vmcnt(8) lgkmcnt(0)
	s_barrier
	v_mfma_f32_16x16x32_bf16 v[60:63], v[146:149], v[182:185], v[60:63]
	v_mfma_f32_16x16x32_bf16 v[56:59], v[158:161], v[182:185], v[56:59]
	v_mfma_f32_16x16x32_bf16 v[44:47], v[146:149], v[190:193], v[44:47]
	v_mfma_f32_16x16x32_bf16 v[40:43], v[158:161], v[190:193], v[40:43]
	v_mfma_f32_16x16x32_bf16 v[28:31], v[146:149], v[198:201], v[28:31]
	v_mfma_f32_16x16x32_bf16 v[24:27], v[158:161], v[198:201], v[24:27]
	v_mfma_f32_16x16x32_bf16 v[12:15], v[146:149], v[206:209], v[12:15]
	v_mfma_f32_16x16x32_bf16 v[8:11], v[158:161], v[206:209], v[8:11]
	v_mfma_f32_16x16x32_bf16 v[60:63], v[154:157], v[186:189], v[60:63]
	v_mfma_f32_16x16x32_bf16 v[56:59], v[162:165], v[186:189], v[56:59]
	v_mfma_f32_16x16x32_bf16 v[44:47], v[154:157], v[194:197], v[44:47]
	v_mfma_f32_16x16x32_bf16 v[40:43], v[162:165], v[194:197], v[40:43]
	v_mfma_f32_16x16x32_bf16 v[28:31], v[154:157], v[202:205], v[28:31]
	v_mfma_f32_16x16x32_bf16 v[24:27], v[162:165], v[202:205], v[24:27]
	v_mfma_f32_16x16x32_bf16 v[12:15], v[154:157], v[210:213], v[12:15]
	v_mfma_f32_16x16x32_bf16 v[8:11], v[162:165], v[210:213], v[8:11]
	v_mfma_f32_16x16x32_bf16 v[52:55], v[166:169], v[182:185], v[52:55]
	v_mfma_f32_16x16x32_bf16 v[48:51], v[174:177], v[182:185], v[48:51]
	v_mfma_f32_16x16x32_bf16 v[36:39], v[166:169], v[190:193], v[36:39]
	v_mfma_f32_16x16x32_bf16 v[32:35], v[174:177], v[190:193], v[32:35]
	v_mfma_f32_16x16x32_bf16 v[20:23], v[166:169], v[198:201], v[20:23]
	v_mfma_f32_16x16x32_bf16 v[16:19], v[174:177], v[198:201], v[16:19]
	v_mfma_f32_16x16x32_bf16 v[4:7], v[166:169], v[206:209], v[4:7]
	v_mfma_f32_16x16x32_bf16 v[0:3], v[174:177], v[206:209], v[0:3]
	v_mfma_f32_16x16x32_bf16 v[52:55], v[170:173], v[186:189], v[52:55]
	v_mfma_f32_16x16x32_bf16 v[48:51], v[178:181], v[186:189], v[48:51]
	v_mfma_f32_16x16x32_bf16 v[36:39], v[170:173], v[194:197], v[36:39]
	v_mfma_f32_16x16x32_bf16 v[32:35], v[178:181], v[194:197], v[32:35]
	v_mfma_f32_16x16x32_bf16 v[20:23], v[170:173], v[202:205], v[20:23]
	v_mfma_f32_16x16x32_bf16 v[16:19], v[178:181], v[202:205], v[16:19]
	v_mfma_f32_16x16x32_bf16 v[4:7], v[170:173], v[210:213], v[4:7]
	v_mfma_f32_16x16x32_bf16 v[0:3], v[178:181], v[210:213], v[0:3]
	s_barrier
	s_setprio 0
	s_add_u32 s30, s30, 0x100
	s_addc_u32 s31, s31, 0
	s_add_u32 s42, s42, 0x100
	s_addc_u32 s43, s43, 0
	s_cmp_ge_u32 s52, s9
	s_mov_b32 s34, s52
	s_cbranch_scc0 .LBB0_506
	s_and_b64 vcc, exec, s[12:13]
	s_cbranch_vccz .LBB0_509

; #define PG8_STAGE(bufoff, gbase, voff) do { _Pragma("unroll") for (int _i = 0; _i < 2; ++_i) \
;         __builtin_amdgcn_global_load_lds((const unsigned*)((const char*)(gbase) + (voff)[_i]), (LAS unsigned*)(lds + (bufoff) + ldsw + _i * 8192), 16, 0, 0); } while (0)
; #define PG8_LDA(dst, b, h) do { _Pragma("unroll") for (int m = 0; m < 4; ++m) _Pragma("unroll") for (int k = 0; k < 2; ++k) dst[m][k] = *(const LAS bf16x8*)(lds + PG8_SA(b, h) + aoff + m * 2048 + k * KOFF); } while (0)
; #define PG8_LDB(dst, b, h) do { _Pragma("unroll") for (int n = 0; n < 2; ++n) _Pragma("unroll") for (int k = 0; k < 2; ++k) dst[n][k] = *(const LAS bf16x8*)(lds + PG8_SB(b, h) + boff + n * 2048 + k * KOFF); } while (0)
; #define PG8_WAIT_V(n) asm volatile("s_waitcnt vmcnt(" #n ")" ::: "memory")
; #define PG8_WAIT_L(n) asm volatile("s_waitcnt lgkmcnt(" #n ")" ::: "memory")
; #define PG8_BAR __builtin_amdgcn_s_barrier()
; #define PG8_SCHED __builtin_amdgcn_sched_barrier(0)
; template <class Epi, bool ALIGN_EPI = true, bool FP8 = false>
; __device__ __forceinline__ void gemm_phase(LAS unsigned char* lds, const Gemm g, const StaticOrder& S, const Epi& E, const int wid) {
;     ...
;             const char* a1 = cA + (size_t)(t + 1) * kstep;
;             const char* a2 = last ? nA : cA + (size_t)(t + 2) * kstep; const char* b2 = last ? nB : cB + (size_t)(t + 2) * kstep;
;             const char* a3 = a2 + kstep; const char* b3 = b2 + kstep;
;             PG8_LDB(B0, 0, 0); PG8_LDB(B1, 0, 1); PG8_SCHED; PG8_LDA(At, 0, 0); PG8_STAGE(PG8_SA(1, 1), a1 + hstep, voffA);
;             PG8_WAIT_V(8); PG8_WAIT_L(0); PG8_BAR; PG8_MMA(0, 0, At, B0); PG8_MMA(0, 1, At, B1); PG8_BAR; PG8_SCHED;
;             PG8_LDA(At, 0, 1); PG8_STAGE(PG8_SB(0, 0), b2, voffB); PG8_STAGE(PG8_SB(0, 1), b2 + hstep, voffB); PG8_STAGE(PG8_SA(0, 0), a2, voffA);
;             PG8_WAIT_V(8); PG8_WAIT_L(0); PG8_BAR; PG8_MMA(1, 0, At, B0); PG8_MMA(1, 1, At, B1); PG8_BAR; PG8_SCHED;
.LBB0_572:
	ds_read_b128 v[152:155], v190
	ds_read_b128 v[156:159], v190 offset:1024
	ds_read_b128 v[144:147], v190 offset:2048
	ds_read_b128 v[148:151], v190 offset:3072
	ds_read_b128 v[136:139], v191
	ds_read_b128 v[140:143], v191 offset:1024
	ds_read_b128 v[128:131], v191 offset:2048
	ds_read_b128 v[132:135], v191 offset:3072
	s_add_i32 s3, s34, 2
	s_add_u32 s35, s30, 0xfffc0080
	s_addc_u32 s36, s31, -1
	s_cmp_eq_u32 s86, s34
	s_cselect_b32 s34, s85, s87
	s_cselect_b32 s37, s21, s36
	s_cselect_b32 s36, s23, s35
	s_cselect_b32 s35, s84, s88
	v_lshl_add_u64 v[220:221], s[30:31], 0, v[170:171]
	s_add_i32 m0, s27, 0xc000
	ds_read_b128 v[178:181], v192
	ds_read_b128 v[182:185], v192 offset:1024
	ds_read_b128 v[196:199], v192 offset:2048
	ds_read_b128 v[200:203], v192 offset:3072
	ds_read_b128 v[204:207], v192 offset:4096
	ds_read_b128 v[208:211], v192 offset:5120
	ds_read_b128 v[212:215], v192 offset:6144
	ds_read_b128 v[216:219], v192 offset:7168
	global_load_lds_dwordx4 v[220:221], off
	v_lshl_add_u64 v[220:221], s[30:31], 0, v[172:173]
	s_add_i32 m0, s27, 0xe000
	s_nop 0
	global_load_lds_dwordx4 v[220:221], off
	s_setprio 1
	s_waitcnt vmcnt(8) lgkmcnt(0)
	s_barrier
	v_mfma_f32_16x16x128_f8f6f4 v[120:123], v[152:159], v[178:185], v[120:123]
	v_mfma_f32_16x16x128_f8f6f4 v[124:127], v[144:151], v[178:185], v[124:127]
	v_mfma_f32_16x16x128_f8f6f4 v[112:115], v[152:159], v[196:203], v[112:115]
	v_mfma_f32_16x16x128_f8f6f4 v[116:119], v[144:151], v[196:203], v[116:119]
	v_mfma_f32_16x16x128_f8f6f4 v[104:107], v[152:159], v[204:211], v[104:107]
	v_mfma_f32_16x16x128_f8f6f4 v[108:111], v[144:151], v[204:211], v[108:111]
	v_mfma_f32_16x16x128_f8f6f4 v[88:91], v[152:159], v[212:219], v[88:91]
	v_mfma_f32_16x16x128_f8f6f4 v[92:95], v[144:151], v[212:219], v[92:95]
	v_mfma_f32_16x16x128_f8f6f4 v[96:99], v[136:143], v[178:185], v[96:99]
	v_mfma_f32_16x16x128_f8f6f4 v[100:103], v[128:135], v[178:185], v[100:103]
	v_mfma_f32_16x16x128_f8f6f4 v[80:83], v[136:143], v[196:203], v[80:83]
	v_mfma_f32_16x16x128_f8f6f4 v[84:87], v[128:135], v[196:203], v[84:87]
	v_mfma_f32_16x16x128_f8f6f4 v[72:75], v[136:143], v[204:211], v[72:75]
	v_mfma_f32_16x16x128_f8f6f4 v[76:79], v[128:135], v[204:211], v[76:79]
	v_mfma_f32_16x16x128_f8f6f4 v[64:67], v[136:143], v[212:219], v[64:67]
	v_mfma_f32_16x16x128_f8f6f4 v[68:71], v[128:135], v[212:219], v[68:71]
	s_barrier
	s_setprio 0
	s_add_i32 s42, s75, s48
	v_lshl_add_u64 v[178:179], s[34:35], 0, v[164:165]
	s_mov_b32 m0, s42
	s_nop 0
	global_load_lds_dwordx4 v[178:179], off
	s_add_i32 m0, s42, 0x2000
	s_add_u32 s42, s34, 0x40000
	v_lshl_add_u64 v[180:181], s[34:35], 0, v[160:161]
	s_addc_u32 s43, s35, 0
	s_add_i32 s52, s76, s48
	global_load_lds_dwordx4 v[180:181], off
	v_lshl_add_u64 v[182:183], s[42:43], 0, v[164:165]
	s_mov_b32 m0, s52
	v_lshl_add_u64 v[184:185], s[36:37], 0, v[162:163]
	global_load_lds_dwordx4 v[182:183], off
	v_lshl_add_u64 v[182:183], s[42:43], 0, v[160:161]
	s_add_i32 m0, s52, 0x2000
	s_nop 0
	global_load_lds_dwordx4 v[182:183], off
	v_lshl_add_u64 v[182:183], s[36:37], 0, v[166:167]
	s_mov_b32 m0, s27
	s_nop 0
	global_load_lds_dwordx4 v[182:183], off
	s_mov_b32 m0, s55
	s_nop 0
	global_load_lds_dwordx4 v[184:185], off
	ds_read_b128 v[196:199], v192 offset:16384
	ds_read_b128 v[200:203], v192 offset:17408
	ds_read_b128 v[204:207], v192 offset:18432
	ds_read_b128 v[208:211], v192 offset:19456
	ds_read_b128 v[212:215], v192 offset:20480
	ds_read_b128 v[216:219], v192 offset:21504
	ds_read_b128 v[220:223], v192 offset:22528
	ds_read_b128 v[224:227], v192 offset:23552
	s_setprio 1
	s_waitcnt vmcnt(8) lgkmcnt(0)
	s_barrier
	v_mfma_f32_16x16x128_f8f6f4 v[56:59], v[152:159], v[196:203], v[56:59]
	v_mfma_f32_16x16x128_f8f6f4 v[60:63], v[144:151], v[196:203], v[60:63]
	v_mfma_f32_16x16x128_f8f6f4 v[48:51], v[152:159], v[204:211], v[48:51]
	v_mfma_f32_16x16x128_f8f6f4 v[52:55], v[144:151], v[204:211], v[52:55]
	v_mfma_f32_16x16x128_f8f6f4 v[40:43], v[152:159], v[212:219], v[40:43]
	v_mfma_f32_16x16x128_f8f6f4 v[44:47], v[144:151], v[212:219], v[44:47]
	v_mfma_f32_16x16x128_f8f6f4 v[228:231], v[152:159], v[220:227], v[24:27]
	v_mfma_f32_16x16x128_f8f6f4 v[232:235], v[144:151], v[220:227], v[28:31]
	v_mfma_f32_16x16x128_f8f6f4 v[236:239], v[136:143], v[196:203], v[32:35]
	v_mfma_f32_16x16x128_f8f6f4 v[240:243], v[128:135], v[196:203], v[36:39]
	v_mfma_f32_16x16x128_f8f6f4 v[244:247], v[136:143], v[204:211], v[16:19]
	v_mfma_f32_16x16x128_f8f6f4 v[204:207], v[128:135], v[204:211], v[20:23]
	v_mfma_f32_16x16x128_f8f6f4 v[208:211], v[136:143], v[212:219], v[8:11]
	v_mfma_f32_16x16x128_f8f6f4 v[212:215], v[128:135], v[212:219], v[12:15]
	v_mfma_f32_16x16x128_f8f6f4 v[216:219], v[136:143], v[220:227], v[0:3]
	v_mfma_f32_16x16x128_f8f6f4 v[220:223], v[128:135], v[220:227], v[4:7]
	s_barrier
	s_setprio 0
	s_add_i32 s42, 0, 0x18000
	s_add_i32 s43, 0, 0x1c000
	s_nop 0
	v_add_u32_e32 v12, s42, v187
	v_add_u32_e32 v16, s43, v187
	ds_read_b128 v[0:3], v12
	ds_read_b128 v[4:7], v12 offset:1024
	ds_read_b128 v[8:11], v12 offset:2048
	ds_read_b128 v[12:15], v12 offset:3072
	ds_read_b128 v[128:131], v16
	ds_read_b128 v[132:135], v16 offset:1024
	ds_read_b128 v[136:139], v16 offset:2048
	ds_read_b128 v[140:143], v16 offset:3072
	s_add_u32 s36, s36, 0x40000
	s_addc_u32 s37, s37, 0
	s_mov_b32 m0, s64
	v_lshl_add_u64 v[152:153], s[36:37], 0, v[166:167]
	ds_read_b128 v[16:19], v192 offset:32768
	ds_read_b128 v[20:23], v192 offset:33792
	ds_read_b128 v[24:27], v192 offset:34816
	ds_read_b128 v[28:31], v192 offset:35840
	ds_read_b128 v[32:35], v192 offset:36864
	ds_read_b128 v[36:39], v192 offset:37888
	ds_read_b128 v[144:147], v192 offset:38912
	ds_read_b128 v[148:151], v192 offset:39936
	global_load_lds_dwordx4 v[152:153], off
	v_lshl_add_u64 v[152:153], s[36:37], 0, v[162:163]
	s_mov_b32 m0, s65
	s_nop 0
	global_load_lds_dwordx4 v[152:153], off
	s_setprio 1
	s_waitcnt vmcnt(8) lgkmcnt(0)
	s_barrier
; #define PG8_STAGE(bufoff, gbase, voff) do { _Pragma("unroll") for (int _i = 0; _i < 2; ++_i) \
;         __builtin_amdgcn_global_load_lds((const unsigned*)((const char*)(gbase) + (voff)[_i]), (LAS unsigned*)(lds + (bufoff) + ldsw + _i * 8192), 16, 0, 0); } while (0)
; #define PG8_LDA(dst, b, h) do { _Pragma("unroll") for (int m = 0; m < 4; ++m) _Pragma("unroll") for (int k = 0; k < 2; ++k) dst[m][k] = *(const LAS bf16x8*)(lds + PG8_SA(b, h) + aoff + m * 2048 + k * KOFF); } while (0)
; #define PG8_WAIT_V(n) asm volatile("s_waitcnt vmcnt(" #n ")" ::: "memory")
; #define PG8_WAIT_L(n) asm volatile("s_waitcnt lgkmcnt(" #n ")" ::: "memory")
; #define PG8_BAR __builtin_amdgcn_s_barrier()
; #define PG8_SCHED __builtin_amdgcn_sched_barrier(0)
; template <class Epi, bool ALIGN_EPI = true, bool FP8 = false>
; __device__ __forceinline__ void gemm_phase(LAS unsigned char* lds, const Gemm g, const StaticOrder& S, const Epi& E, const int wid) {
;     ...
;             PG8_WAIT_V(8); PG8_WAIT_L(0); PG8_BAR; PG8_MMA(0, 0, At, B0); PG8_MMA(0, 1, At, B1); PG8_BAR; PG8_SCHED;
;             PG8_LDA(At, 1, 1); PG8_STAGE(PG8_SB(1, 0), b3, voffB); PG8_STAGE(PG8_SB(1, 1), b3 + hstep, voffB); PG8_STAGE(PG8_SA(1, 0), a3, voffA);
;             PG8_WAIT_V(8); PG8_WAIT_L(0); PG8_BAR; PG8_MMA(1, 0, At, B0); PG8_MMA(1, 1, At, B1); PG8_BAR; PG8_SCHED;
;         }
	v_mfma_f32_16x16x128_f8f6f4 v[120:123], v[0:7], v[16:23], v[120:123]
	v_mfma_f32_16x16x128_f8f6f4 v[124:127], v[8:15], v[16:23], v[124:127]
	v_mfma_f32_16x16x128_f8f6f4 v[112:115], v[0:7], v[24:31], v[112:115]
	v_mfma_f32_16x16x128_f8f6f4 v[116:119], v[8:15], v[24:31], v[116:119]
	v_mfma_f32_16x16x128_f8f6f4 v[104:107], v[0:7], v[32:39], v[104:107]
	v_mfma_f32_16x16x128_f8f6f4 v[108:111], v[8:15], v[32:39], v[108:111]
	v_mfma_f32_16x16x128_f8f6f4 v[88:91], v[0:7], v[144:151], v[88:91]
	v_mfma_f32_16x16x128_f8f6f4 v[92:95], v[8:15], v[144:151], v[92:95]
	v_mfma_f32_16x16x128_f8f6f4 v[96:99], v[128:135], v[16:23], v[96:99]
	v_mfma_f32_16x16x128_f8f6f4 v[100:103], v[136:143], v[16:23], v[100:103]
	v_mfma_f32_16x16x128_f8f6f4 v[80:83], v[128:135], v[24:31], v[80:83]
	v_mfma_f32_16x16x128_f8f6f4 v[84:87], v[136:143], v[24:31], v[84:87]
	v_mfma_f32_16x16x128_f8f6f4 v[72:75], v[128:135], v[32:39], v[72:75]
	v_mfma_f32_16x16x128_f8f6f4 v[76:79], v[136:143], v[32:39], v[76:79]
	v_mfma_f32_16x16x128_f8f6f4 v[64:67], v[128:135], v[144:151], v[64:67]
	v_mfma_f32_16x16x128_f8f6f4 v[68:71], v[136:143], v[144:151], v[68:71]
	s_barrier
	s_setprio 0
	s_add_i32 s36, s42, s48
	v_lshl_add_u64 v[24:25], v[178:179], 0, s[8:9]
	s_mov_b32 m0, s36
	s_nop 0
	global_load_lds_dwordx4 v[24:25], off
	s_add_i32 m0, s36, 0x2000
	s_add_u32 s34, s34, 0x40080
	v_lshl_add_u64 v[24:25], v[180:181], 0, s[8:9]
	s_addc_u32 s35, s35, 0
	s_add_i32 s36, s43, s48
	global_load_lds_dwordx4 v[24:25], off
	v_lshl_add_u64 v[24:25], s[34:35], 0, v[164:165]
	s_mov_b32 m0, s36
	s_nop 0
	global_load_lds_dwordx4 v[24:25], off
	v_lshl_add_u64 v[24:25], s[34:35], 0, v[160:161]
	s_add_i32 m0, s36, 0x2000
	s_nop 0
	global_load_lds_dwordx4 v[24:25], off
	v_lshl_add_u64 v[24:25], v[182:183], 0, s[8:9]
	s_mov_b32 m0, s70
	s_nop 0
	global_load_lds_dwordx4 v[24:25], off
	v_lshl_add_u64 v[24:25], v[184:185], 0, s[8:9]
	s_mov_b32 m0, s71
	s_nop 0
	global_load_lds_dwordx4 v[24:25], off
	ds_read_b128 v[16:19], v192 offset:49152
	ds_read_b128 v[20:23], v192 offset:50176
	ds_read_b128 v[144:147], v192 offset:51200
	ds_read_b128 v[148:151], v192 offset:52224
	ds_read_b128 v[152:155], v192 offset:53248
	ds_read_b128 v[156:159], v192 offset:54272
	ds_read_b128 v[196:199], v192 offset:55296
	ds_read_b128 v[200:203], v192 offset:56320
	s_setprio 1
	s_waitcnt vmcnt(8) lgkmcnt(0)
	s_barrier
	v_mfma_f32_16x16x128_f8f6f4 v[56:59], v[0:7], v[16:23], v[56:59]
	v_mfma_f32_16x16x128_f8f6f4 v[60:63], v[8:15], v[16:23], v[60:63]
	v_mfma_f32_16x16x128_f8f6f4 v[48:51], v[0:7], v[144:151], v[48:51]
	v_mfma_f32_16x16x128_f8f6f4 v[52:55], v[8:15], v[144:151], v[52:55]
	v_mfma_f32_16x16x128_f8f6f4 v[40:43], v[0:7], v[152:159], v[40:43]
	v_mfma_f32_16x16x128_f8f6f4 v[44:47], v[8:15], v[152:159], v[44:47]
	v_mfma_f32_16x16x128_f8f6f4 v[24:27], v[0:7], v[196:203], v[228:231]
	v_mfma_f32_16x16x128_f8f6f4 v[28:31], v[8:15], v[196:203], v[232:235]
	v_mfma_f32_16x16x128_f8f6f4 v[32:35], v[128:135], v[16:23], v[236:239]
	v_mfma_f32_16x16x128_f8f6f4 v[36:39], v[136:143], v[16:23], v[240:243]
	v_mfma_f32_16x16x128_f8f6f4 v[16:19], v[128:135], v[144:151], v[244:247]
	v_mfma_f32_16x16x128_f8f6f4 v[20:23], v[136:143], v[144:151], v[204:207]
	v_mfma_f32_16x16x128_f8f6f4 v[8:11], v[128:135], v[152:159], v[208:211]
	v_mfma_f32_16x16x128_f8f6f4 v[12:15], v[136:143], v[152:159], v[212:215]
	v_mfma_f32_16x16x128_f8f6f4 v[0:3], v[128:135], v[196:203], v[216:219]
	v_mfma_f32_16x16x128_f8f6f4 v[4:7], v[136:143], v[196:203], v[220:223]
	s_barrier
	s_setprio 0
	s_add_u32 s30, s30, 0x100
	s_addc_u32 s31, s31, 0
	s_add_u32 s87, s87, 0x100
	s_addc_u32 s88, s88, 0
	s_cmp_ge_u32 s3, s83
	s_mov_b32 s34, s3
	s_cbranch_scc0 .LBB0_572
;     __device__ __forceinline__ void operator()(const Acc& acc, const Unit& u, int wr, int wc, int fr, int fq) const {
;     ...
;                         const f32x4 v0 = acc[ai][bj][m][0] * QS, v1 = acc[ai][bj][m][1] * QS;
; template <class Epi, bool ALIGN_EPI = true, bool FP8 = false>
; __device__ __forceinline__ void gemm_phase(LAS unsigned char* lds, const Gemm g, const StaticOrder& S, const Epi& E, const int wid) {
;     ...
;         if constexpr (FP8) {
; #pragma unroll
;             for (int a = 0; a < 2; ++a)
; #pragma unroll
;                 for (int b = 0; b < 2; ++b)
; #pragma unroll
;                     for (int m = 0; m < 4; ++m) { const f32x8 c_ = acc8[a][b][m]; acc[a][b][m][0] = __builtin_shufflevector(c_, c_, 0, 1, 2, 3); acc[a][b][m][1] = __builtin_shufflevector(c_, c_, 4, 5, 6, 7); }
;         }
	v_pk_mul_f32 v[122:123], v[122:123], s[14:15] op_sel_hi:[1,0]
	v_pk_mul_f32 v[128:129], v[120:121], s[14:15] op_sel_hi:[1,0]
	v_pk_mul_f32 v[120:121], v[126:127], s[14:15] op_sel_hi:[1,0]
	v_pk_mul_f32 v[124:125], v[124:125], s[14:15] op_sel_hi:[1,0]
	v_pk_mul_f32 v[132:133], v[98:99], s[14:15] op_sel_hi:[1,0]
	v_pk_mul_f32 v[136:137], v[96:97], s[14:15] op_sel_hi:[1,0]
	v_pk_mul_f32 v[130:131], v[102:103], s[14:15] op_sel_hi:[1,0]
	v_pk_mul_f32 v[134:135], v[100:101], s[14:15] op_sel_hi:[1,0]
	v_pk_mul_f32 v[100:101], v[114:115], s[14:15] op_sel_hi:[1,0]
	v_pk_mul_f32 v[112:113], v[112:113], s[14:15] op_sel_hi:[1,0]
	v_pk_mul_f32 v[96:97], v[118:119], s[14:15] op_sel_hi:[1,0]
	v_pk_mul_f32 v[102:103], v[116:117], s[14:15] op_sel_hi:[1,0]
	v_pk_mul_f32 v[116:117], v[82:83], s[14:15] op_sel_hi:[1,0]
	v_pk_mul_f32 v[126:127], v[80:81], s[14:15] op_sel_hi:[1,0]
	v_pk_mul_f32 v[114:115], v[86:87], s[14:15] op_sel_hi:[1,0]
	v_pk_mul_f32 v[118:119], v[84:85], s[14:15] op_sel_hi:[1,0]
	v_pk_mul_f32 v[82:83], v[106:107], s[14:15] op_sel_hi:[1,0]
	v_pk_mul_f32 v[86:87], v[104:105], s[14:15] op_sel_hi:[1,0]
	v_pk_mul_f32 v[80:81], v[110:111], s[14:15] op_sel_hi:[1,0]
	v_pk_mul_f32 v[84:85], v[108:109], s[14:15] op_sel_hi:[1,0]
	v_pk_mul_f32 v[104:105], v[74:75], s[14:15] op_sel_hi:[1,0]
	v_pk_mul_f32 v[108:109], v[72:73], s[14:15] op_sel_hi:[1,0]
	v_pk_mul_f32 v[98:99], v[78:79], s[14:15] op_sel_hi:[1,0]
	v_pk_mul_f32 v[106:107], v[76:77], s[14:15] op_sel_hi:[1,0]
	v_pk_mul_f32 v[74:75], v[90:91], s[14:15] op_sel_hi:[1,0]
	v_pk_mul_f32 v[78:79], v[88:89], s[14:15] op_sel_hi:[1,0]
	v_pk_mul_f32 v[72:73], v[94:95], s[14:15] op_sel_hi:[1,0]
	v_pk_mul_f32 v[76:77], v[92:93], s[14:15] op_sel_hi:[1,0]
	v_pk_mul_f32 v[66:67], v[66:67], s[14:15] op_sel_hi:[1,0]
	v_pk_mul_f32 v[88:89], v[64:65], s[14:15] op_sel_hi:[1,0]
	v_pk_mul_f32 v[64:65], v[70:71], s[14:15] op_sel_hi:[1,0]
	v_pk_mul_f32 v[68:69], v[68:69], s[14:15] op_sel_hi:[1,0]
	v_pk_mul_f32 v[58:59], v[58:59], s[14:15] op_sel_hi:[1,0]
	v_pk_mul_f32 v[70:71], v[56:57], s[14:15] op_sel_hi:[1,0]
	v_pk_mul_f32 v[56:57], v[62:63], s[14:15] op_sel_hi:[1,0]
	v_pk_mul_f32 v[60:61], v[60:61], s[14:15] op_sel_hi:[1,0]
	v_pk_mul_f32 v[92:93], v[34:35], s[14:15] op_sel_hi:[1,0]
	v_pk_mul_f32 v[110:111], v[32:33], s[14:15] op_sel_hi:[1,0]
	v_pk_mul_f32 v[90:91], v[38:39], s[14:15] op_sel_hi:[1,0]
	v_pk_mul_f32 v[94:95], v[36:37], s[14:15] op_sel_hi:[1,0]
	v_pk_mul_f32 v[36:37], v[50:51], s[14:15] op_sel_hi:[1,0]
	v_pk_mul_f32 v[48:49], v[48:49], s[14:15] op_sel_hi:[1,0]
	v_pk_mul_f32 v[32:33], v[54:55], s[14:15] op_sel_hi:[1,0]
	v_pk_mul_f32 v[38:39], v[52:53], s[14:15] op_sel_hi:[1,0]
	v_pk_mul_f32 v[52:53], v[18:19], s[14:15] op_sel_hi:[1,0]
	v_pk_mul_f32 v[62:63], v[16:17], s[14:15] op_sel_hi:[1,0]
	v_pk_mul_f32 v[50:51], v[22:23], s[14:15] op_sel_hi:[1,0]
	v_pk_mul_f32 v[54:55], v[20:21], s[14:15] op_sel_hi:[1,0]
	v_pk_mul_f32 v[18:19], v[42:43], s[14:15] op_sel_hi:[1,0]
	v_pk_mul_f32 v[22:23], v[40:41], s[14:15] op_sel_hi:[1,0]
	v_pk_mul_f32 v[16:17], v[46:47], s[14:15] op_sel_hi:[1,0]
	v_pk_mul_f32 v[20:21], v[44:45], s[14:15] op_sel_hi:[1,0]
	v_pk_mul_f32 v[40:41], v[10:11], s[14:15] op_sel_hi:[1,0]
	v_pk_mul_f32 v[44:45], v[8:9], s[14:15] op_sel_hi:[1,0]
	v_pk_mul_f32 v[34:35], v[14:15], s[14:15] op_sel_hi:[1,0]
	v_pk_mul_f32 v[42:43], v[12:13], s[14:15] op_sel_hi:[1,0]
	v_pk_mul_f32 v[10:11], v[26:27], s[14:15] op_sel_hi:[1,0]
	v_pk_mul_f32 v[14:15], v[24:25], s[14:15] op_sel_hi:[1,0]
	v_pk_mul_f32 v[8:9], v[30:31], s[14:15] op_sel_hi:[1,0]
	v_pk_mul_f32 v[12:13], v[28:29], s[14:15] op_sel_hi:[1,0]
	v_pk_mul_f32 v[2:3], v[2:3], s[14:15] op_sel_hi:[1,0]
	v_pk_mul_f32 v[24:25], v[0:1], s[14:15] op_sel_hi:[1,0]
	v_pk_mul_f32 v[0:1], v[6:7], s[14:15] op_sel_hi:[1,0]
	v_pk_mul_f32 v[4:5], v[4:5], s[14:15] op_sel_hi:[1,0]
	s_and_b64 vcc, exec, s[12:13]
	s_cbranch_vccz .LBB0_575

; #define PG8_STAGE(bufoff, gbase, voff) do { _Pragma("unroll") for (int _i = 0; _i < 2; ++_i) \
;         __builtin_amdgcn_global_load_lds((const unsigned*)((const char*)(gbase) + (voff)[_i]), (LAS unsigned*)(lds + (bufoff) + ldsw + _i * 8192), 16, 0, 0); } while (0)
; #define PG8_LDA(dst, b, h) do { _Pragma("unroll") for (int m = 0; m < 4; ++m) _Pragma("unroll") for (int k = 0; k < 2; ++k) dst[m][k] = *(const LAS bf16x8*)(lds + PG8_SA(b, h) + aoff + m * 2048 + k * KOFF); } while (0)
; #define PG8_LDB(dst, b, h) do { _Pragma("unroll") for (int n = 0; n < 2; ++n) _Pragma("unroll") for (int k = 0; k < 2; ++k) dst[n][k] = *(const LAS bf16x8*)(lds + PG8_SB(b, h) + boff + n * 2048 + k * KOFF); } while (0)
; #define PG8_WAIT_V(n) asm volatile("s_waitcnt vmcnt(" #n ")" ::: "memory")
; #define PG8_WAIT_L(n) asm volatile("s_waitcnt lgkmcnt(" #n ")" ::: "memory")
; #define PG8_BAR __builtin_amdgcn_s_barrier()
; #define PG8_SCHED __builtin_amdgcn_sched_barrier(0)
; template <class Epi, bool ALIGN_EPI = true, bool FP8 = false>
; __device__ __forceinline__ void gemm_phase(LAS unsigned char* lds, const Gemm g, const StaticOrder& S, const Epi& E, const int wid) {
;     ...
;             const char* a1 = cA + (size_t)(t + 1) * kstep;
;             const char* a2 = last ? nA : cA + (size_t)(t + 2) * kstep; const char* b2 = last ? nB : cB + (size_t)(t + 2) * kstep;
;             const char* a3 = a2 + kstep; const char* b3 = b2 + kstep;
;             PG8_LDB(B0, 0, 0); PG8_LDB(B1, 0, 1); PG8_SCHED; PG8_LDA(At, 0, 0); PG8_STAGE(PG8_SA(1, 1), a1 + hstep, voffA);
;             PG8_WAIT_V(8); PG8_WAIT_L(0); PG8_BAR; PG8_MMA(0, 0, At, B0); PG8_MMA(0, 1, At, B1); PG8_BAR; PG8_SCHED;
;             PG8_LDA(At, 0, 1); PG8_STAGE(PG8_SB(0, 0), b2, voffB); PG8_STAGE(PG8_SB(0, 1), b2 + hstep, voffB); PG8_STAGE(PG8_SA(0, 0), a2, voffA);
;             PG8_WAIT_V(8); PG8_WAIT_L(0); PG8_BAR; PG8_MMA(1, 0, At, B0); PG8_MMA(1, 1, At, B1); PG8_BAR; PG8_SCHED;
.LBB0_2058:
	v_add_u32_e32 v128, s83, v192
	v_add_u32_e32 v132, s84, v192
	ds_read_b128 v[152:155], v128
	ds_read_b128 v[156:159], v128 offset:1024
	ds_read_b128 v[144:147], v128 offset:2048
	ds_read_b128 v[148:151], v128 offset:3072
	ds_read_b128 v[136:139], v132
	ds_read_b128 v[140:143], v132 offset:1024
	ds_read_b128 v[128:131], v132 offset:2048
	ds_read_b128 v[132:135], v132 offset:3072
	s_add_i32 s3, s42, 2
	s_add_u32 s43, s64, 0xfffe0080
	s_addc_u32 s52, s65, -1
	s_cmp_eq_u32 s35, s42
	s_cselect_b32 s69, s11, s52
	s_cselect_b32 s68, s16, s43
	s_cselect_b32 s67, s29, s90
	s_cselect_b32 s66, s31, s89
	v_lshl_add_u64 v[188:189], s[64:65], 0, v[174:175]
	s_add_i32 m0, s72, 0xc000
	ds_read_b128 v[180:183], v193
	ds_read_b128 v[184:187], v193 offset:1024
	ds_read_b128 v[196:199], v193 offset:2048
	ds_read_b128 v[200:203], v193 offset:3072
	ds_read_b128 v[204:207], v193 offset:4096
	ds_read_b128 v[208:211], v193 offset:5120
	ds_read_b128 v[212:215], v193 offset:6144
	ds_read_b128 v[216:219], v193 offset:7168
	global_load_lds_dwordx4 v[188:189], off
	v_lshl_add_u64 v[188:189], s[64:65], 0, v[176:177]
	s_add_i32 m0, s72, 0xe000
	s_nop 0
	global_load_lds_dwordx4 v[188:189], off
	s_setprio 1
	s_waitcnt vmcnt(8) lgkmcnt(0)
	s_barrier
	v_mfma_f32_16x16x128_f8f6f4 v[120:123], v[152:159], v[180:187], v[120:123]
	v_mfma_f32_16x16x128_f8f6f4 v[124:127], v[144:151], v[180:187], v[124:127]
	v_mfma_f32_16x16x128_f8f6f4 v[112:115], v[152:159], v[196:203], v[112:115]
	v_mfma_f32_16x16x128_f8f6f4 v[116:119], v[144:151], v[196:203], v[116:119]
	v_mfma_f32_16x16x128_f8f6f4 v[104:107], v[152:159], v[204:211], v[104:107]
	v_mfma_f32_16x16x128_f8f6f4 v[108:111], v[144:151], v[204:211], v[108:111]
	v_mfma_f32_16x16x128_f8f6f4 v[96:99], v[152:159], v[212:219], v[96:99]
	v_mfma_f32_16x16x128_f8f6f4 v[100:103], v[144:151], v[212:219], v[100:103]
	v_mfma_f32_16x16x128_f8f6f4 v[88:91], v[136:143], v[180:187], v[88:91]
	v_mfma_f32_16x16x128_f8f6f4 v[92:95], v[128:135], v[180:187], v[92:95]
	v_mfma_f32_16x16x128_f8f6f4 v[80:83], v[136:143], v[196:203], v[80:83]
	v_mfma_f32_16x16x128_f8f6f4 v[84:87], v[128:135], v[196:203], v[84:87]
	v_mfma_f32_16x16x128_f8f6f4 v[72:75], v[136:143], v[204:211], v[72:75]
	v_mfma_f32_16x16x128_f8f6f4 v[76:79], v[128:135], v[204:211], v[76:79]
	v_mfma_f32_16x16x128_f8f6f4 v[64:67], v[136:143], v[212:219], v[64:67]
	v_mfma_f32_16x16x128_f8f6f4 v[68:71], v[128:135], v[212:219], v[68:71]
	s_barrier
	s_setprio 0
	s_add_i32 s42, s83, s71
	v_lshl_add_u64 v[180:181], s[66:67], 0, v[162:163]
	s_mov_b32 m0, s42
	s_nop 0
	global_load_lds_dwordx4 v[180:181], off
	s_add_i32 m0, s42, 0x2000
	s_add_u32 s42, s66, 0x20000
	v_lshl_add_u64 v[182:183], s[66:67], 0, v[166:167]
	s_addc_u32 s43, s67, 0
	s_add_i32 s52, s84, s71
	global_load_lds_dwordx4 v[182:183], off
	v_lshl_add_u64 v[184:185], s[42:43], 0, v[162:163]
	s_mov_b32 m0, s52
	v_lshl_add_u64 v[186:187], s[68:69], 0, v[164:165]
	global_load_lds_dwordx4 v[184:185], off
	v_lshl_add_u64 v[184:185], s[42:43], 0, v[166:167]
	s_add_i32 m0, s52, 0x2000
	s_nop 0
	global_load_lds_dwordx4 v[184:185], off
	v_lshl_add_u64 v[184:185], s[68:69], 0, v[160:161]
	s_mov_b32 m0, s72
	s_nop 0
	global_load_lds_dwordx4 v[184:185], off
	s_mov_b32 m0, s73
	s_nop 0
	global_load_lds_dwordx4 v[186:187], off
	ds_read_b128 v[196:199], v193 offset:16384
	ds_read_b128 v[200:203], v193 offset:17408
	ds_read_b128 v[204:207], v193 offset:18432
	ds_read_b128 v[208:211], v193 offset:19456
	ds_read_b128 v[212:215], v193 offset:20480
	ds_read_b128 v[216:219], v193 offset:21504
	ds_read_b128 v[220:223], v193 offset:22528
	ds_read_b128 v[224:227], v193 offset:23552
	s_setprio 1
	s_waitcnt vmcnt(8) lgkmcnt(0)
	s_barrier
	v_mfma_f32_16x16x128_f8f6f4 v[56:59], v[152:159], v[196:203], v[56:59]
	v_mfma_f32_16x16x128_f8f6f4 v[60:63], v[144:151], v[196:203], v[60:63]
	v_mfma_f32_16x16x128_f8f6f4 v[48:51], v[152:159], v[204:211], v[48:51]
	v_mfma_f32_16x16x128_f8f6f4 v[52:55], v[144:151], v[204:211], v[52:55]
	v_mfma_f32_16x16x128_f8f6f4 v[40:43], v[152:159], v[212:219], v[40:43]
	v_mfma_f32_16x16x128_f8f6f4 v[44:47], v[144:151], v[212:219], v[44:47]
	v_mfma_f32_16x16x128_f8f6f4 v[188:191], v[152:159], v[220:227], v[32:35]
	v_mfma_f32_16x16x128_f8f6f4 v[228:231], v[144:151], v[220:227], v[36:39]
	v_mfma_f32_16x16x128_f8f6f4 v[232:235], v[136:143], v[196:203], v[24:27]
	v_mfma_f32_16x16x128_f8f6f4 v[236:239], v[128:135], v[196:203], v[28:31]
	v_mfma_f32_16x16x128_f8f6f4 v[240:243], v[136:143], v[204:211], v[16:19]
	v_mfma_f32_16x16x128_f8f6f4 v[204:207], v[128:135], v[204:211], v[20:23]
	v_mfma_f32_16x16x128_f8f6f4 v[208:211], v[136:143], v[212:219], v[8:11]
	v_mfma_f32_16x16x128_f8f6f4 v[212:215], v[128:135], v[212:219], v[12:15]
	v_mfma_f32_16x16x128_f8f6f4 v[216:219], v[136:143], v[220:227], v[0:3]
	v_mfma_f32_16x16x128_f8f6f4 v[220:223], v[128:135], v[220:227], v[4:7]
	s_barrier
; #define PG8_STAGE(bufoff, gbase, voff) do { _Pragma("unroll") for (int _i = 0; _i < 2; ++_i) \
;         __builtin_amdgcn_global_load_lds((const unsigned*)((const char*)(gbase) + (voff)[_i]), (LAS unsigned*)(lds + (bufoff) + ldsw + _i * 8192), 16, 0, 0); } while (0)
; #define PG8_LDA(dst, b, h) do { _Pragma("unroll") for (int m = 0; m < 4; ++m) _Pragma("unroll") for (int k = 0; k < 2; ++k) dst[m][k] = *(const LAS bf16x8*)(lds + PG8_SA(b, h) + aoff + m * 2048 + k * KOFF); } while (0)
; #define PG8_LDB(dst, b, h) do { _Pragma("unroll") for (int n = 0; n < 2; ++n) _Pragma("unroll") for (int k = 0; k < 2; ++k) dst[n][k] = *(const LAS bf16x8*)(lds + PG8_SB(b, h) + boff + n * 2048 + k * KOFF); } while (0)
; #define PG8_WAIT_V(n) asm volatile("s_waitcnt vmcnt(" #n ")" ::: "memory")
; #define PG8_WAIT_L(n) asm volatile("s_waitcnt lgkmcnt(" #n ")" ::: "memory")
; #define PG8_BAR __builtin_amdgcn_s_barrier()
; #define PG8_SCHED __builtin_amdgcn_sched_barrier(0)
; template <class Epi, bool ALIGN_EPI = true, bool FP8 = false>
; __device__ __forceinline__ void gemm_phase(LAS unsigned char* lds, const Gemm g, const StaticOrder& S, const Epi& E, const int wid) {
;     ...
;             PG8_LDB(B0, 1, 0); PG8_LDB(B1, 1, 1); PG8_SCHED; PG8_LDA(At, 1, 0); PG8_STAGE(PG8_SA(0, 1), a2 + hstep, voffA);
;             PG8_WAIT_V(8); PG8_WAIT_L(0); PG8_BAR; PG8_MMA(0, 0, At, B0); PG8_MMA(0, 1, At, B1); PG8_BAR; PG8_SCHED;
;             PG8_LDA(At, 1, 1); PG8_STAGE(PG8_SB(1, 0), b3, voffB); PG8_STAGE(PG8_SB(1, 1), b3 + hstep, voffB); PG8_STAGE(PG8_SA(1, 0), a3, voffA);
;             PG8_WAIT_V(8); PG8_WAIT_L(0); PG8_BAR; PG8_MMA(1, 0, At, B0); PG8_MMA(1, 1, At, B1); PG8_BAR; PG8_SCHED;
	s_setprio 0
	s_add_i32 s52, 0, 0x18000
	s_add_i32 s54, 0, 0x1c000
	s_nop 0
	v_add_u32_e32 v12, s52, v192
	v_add_u32_e32 v16, s54, v192
	ds_read_b128 v[0:3], v12
	ds_read_b128 v[4:7], v12 offset:1024
	ds_read_b128 v[8:11], v12 offset:2048
	ds_read_b128 v[12:15], v12 offset:3072
	ds_read_b128 v[128:131], v16
	ds_read_b128 v[132:135], v16 offset:1024
	ds_read_b128 v[136:139], v16 offset:2048
	ds_read_b128 v[140:143], v16 offset:3072
	s_add_u32 s42, s68, 0x20000
	s_addc_u32 s43, s69, 0
	s_mov_b32 m0, s74
	v_lshl_add_u64 v[152:153], s[42:43], 0, v[160:161]
	ds_read_b128 v[16:19], v193 offset:32768
	ds_read_b128 v[20:23], v193 offset:33792
	ds_read_b128 v[24:27], v193 offset:34816
	ds_read_b128 v[28:31], v193 offset:35840
	ds_read_b128 v[32:35], v193 offset:36864
	ds_read_b128 v[36:39], v193 offset:37888
	ds_read_b128 v[144:147], v193 offset:38912
	ds_read_b128 v[148:151], v193 offset:39936
	global_load_lds_dwordx4 v[152:153], off
	v_lshl_add_u64 v[152:153], s[42:43], 0, v[164:165]
	s_mov_b32 m0, s75
	s_nop 0
	global_load_lds_dwordx4 v[152:153], off
	s_setprio 1
	s_waitcnt vmcnt(8) lgkmcnt(0)
	s_barrier
	v_mfma_f32_16x16x128_f8f6f4 v[120:123], v[0:7], v[16:23], v[120:123]
	v_mfma_f32_16x16x128_f8f6f4 v[124:127], v[8:15], v[16:23], v[124:127]
	v_mfma_f32_16x16x128_f8f6f4 v[112:115], v[0:7], v[24:31], v[112:115]
	v_mfma_f32_16x16x128_f8f6f4 v[116:119], v[8:15], v[24:31], v[116:119]
	v_mfma_f32_16x16x128_f8f6f4 v[104:107], v[0:7], v[32:39], v[104:107]
	v_mfma_f32_16x16x128_f8f6f4 v[108:111], v[8:15], v[32:39], v[108:111]
	v_mfma_f32_16x16x128_f8f6f4 v[96:99], v[0:7], v[144:151], v[96:99]
	v_mfma_f32_16x16x128_f8f6f4 v[100:103], v[8:15], v[144:151], v[100:103]
	v_mfma_f32_16x16x128_f8f6f4 v[88:91], v[128:135], v[16:23], v[88:91]
	v_mfma_f32_16x16x128_f8f6f4 v[92:95], v[136:143], v[16:23], v[92:95]
	v_mfma_f32_16x16x128_f8f6f4 v[80:83], v[128:135], v[24:31], v[80:83]
	v_mfma_f32_16x16x128_f8f6f4 v[84:87], v[136:143], v[24:31], v[84:87]
	v_mfma_f32_16x16x128_f8f6f4 v[72:75], v[128:135], v[32:39], v[72:75]
	v_mfma_f32_16x16x128_f8f6f4 v[76:79], v[136:143], v[32:39], v[76:79]
	v_mfma_f32_16x16x128_f8f6f4 v[64:67], v[128:135], v[144:151], v[64:67]
	v_mfma_f32_16x16x128_f8f6f4 v[68:71], v[136:143], v[144:151], v[68:71]
	s_barrier
	s_setprio 0
	s_add_i32 s42, s52, s71
	v_lshl_add_u64 v[24:25], v[180:181], 0, s[20:21]
	s_mov_b32 m0, s42
	s_nop 0
	global_load_lds_dwordx4 v[24:25], off
	s_add_i32 m0, s42, 0x2000
	s_add_u32 s42, s66, 0x20080
	v_lshl_add_u64 v[24:25], v[182:183], 0, s[20:21]
	s_addc_u32 s43, s67, 0
	s_add_i32 s52, s54, s71
	global_load_lds_dwordx4 v[24:25], off
	v_lshl_add_u64 v[24:25], s[42:43], 0, v[162:163]
	s_mov_b32 m0, s52
	s_nop 0
	global_load_lds_dwordx4 v[24:25], off
	v_lshl_add_u64 v[24:25], s[42:43], 0, v[166:167]
	s_add_i32 m0, s52, 0x2000
	s_nop 0
	global_load_lds_dwordx4 v[24:25], off
	v_lshl_add_u64 v[24:25], v[184:185], 0, s[20:21]
	s_mov_b32 m0, s80
	s_nop 0
	global_load_lds_dwordx4 v[24:25], off
	v_lshl_add_u64 v[24:25], v[186:187], 0, s[20:21]
	s_mov_b32 m0, s81
	s_nop 0
	global_load_lds_dwordx4 v[24:25], off
	ds_read_b128 v[16:19], v193 offset:49152
	ds_read_b128 v[20:23], v193 offset:50176
	ds_read_b128 v[144:147], v193 offset:51200
	ds_read_b128 v[148:151], v193 offset:52224
	ds_read_b128 v[152:155], v193 offset:53248
	ds_read_b128 v[156:159], v193 offset:54272
	ds_read_b128 v[196:199], v193 offset:55296
	ds_read_b128 v[200:203], v193 offset:56320
	s_setprio 1
	s_waitcnt vmcnt(8) lgkmcnt(0)
	s_barrier
	v_mfma_f32_16x16x128_f8f6f4 v[56:59], v[0:7], v[16:23], v[56:59]
	v_mfma_f32_16x16x128_f8f6f4 v[60:63], v[8:15], v[16:23], v[60:63]
	v_mfma_f32_16x16x128_f8f6f4 v[48:51], v[0:7], v[144:151], v[48:51]
	v_mfma_f32_16x16x128_f8f6f4 v[52:55], v[8:15], v[144:151], v[52:55]
	v_mfma_f32_16x16x128_f8f6f4 v[40:43], v[0:7], v[152:159], v[40:43]
	v_mfma_f32_16x16x128_f8f6f4 v[44:47], v[8:15], v[152:159], v[44:47]
	v_mfma_f32_16x16x128_f8f6f4 v[32:35], v[0:7], v[196:203], v[188:191]
	v_mfma_f32_16x16x128_f8f6f4 v[36:39], v[8:15], v[196:203], v[228:231]
	v_mfma_f32_16x16x128_f8f6f4 v[24:27], v[128:135], v[16:23], v[232:235]
	v_mfma_f32_16x16x128_f8f6f4 v[28:31], v[136:143], v[16:23], v[236:239]
	v_mfma_f32_16x16x128_f8f6f4 v[16:19], v[128:135], v[144:151], v[240:243]
	v_mfma_f32_16x16x128_f8f6f4 v[20:23], v[136:143], v[144:151], v[204:207]
	v_mfma_f32_16x16x128_f8f6f4 v[8:11], v[128:135], v[152:159], v[208:211]
	v_mfma_f32_16x16x128_f8f6f4 v[12:15], v[136:143], v[152:159], v[212:215]
	v_mfma_f32_16x16x128_f8f6f4 v[0:3], v[128:135], v[196:203], v[216:219]
	v_mfma_f32_16x16x128_f8f6f4 v[4:7], v[136:143], v[196:203], v[220:223]
	s_barrier
	s_setprio 0
	s_add_u32 s64, s64, 0x100
	s_addc_u32 s65, s65, 0
	s_add_u32 s89, s89, 0x100
	s_addc_u32 s90, s90, 0
	s_cmp_ge_u32 s3, s9
	s_mov_b32 s42, s3
	s_cbranch_scc0 .LBB0_2058
	s_and_b64 vcc, exec, s[22:23]
	s_cbranch_vccz .LBB0_2061
	s_barrier

; #define PG8_STAGE(bufoff, gbase, voff) do { _Pragma("unroll") for (int _i = 0; _i < 2; ++_i) \
;         __builtin_amdgcn_global_load_lds((const unsigned*)((const char*)(gbase) + (voff)[_i]), (LAS unsigned*)(lds + (bufoff) + ldsw + _i * 8192), 16, 0, 0); } while (0)
; #define PG8_LDA(dst, b, h) do { _Pragma("unroll") for (int m = 0; m < 4; ++m) _Pragma("unroll") for (int k = 0; k < 2; ++k) dst[m][k] = *(const LAS bf16x8*)(lds + PG8_SA(b, h) + aoff + m * 2048 + k * KOFF); } while (0)
; #define PG8_LDB(dst, b, h) do { _Pragma("unroll") for (int n = 0; n < 2; ++n) _Pragma("unroll") for (int k = 0; k < 2; ++k) dst[n][k] = *(const LAS bf16x8*)(lds + PG8_SB(b, h) + boff + n * 2048 + k * KOFF); } while (0)
; #define PG8_WAIT_V(n) asm volatile("s_waitcnt vmcnt(" #n ")" ::: "memory")
; #define PG8_WAIT_L(n) asm volatile("s_waitcnt lgkmcnt(" #n ")" ::: "memory")
; #define PG8_BAR __builtin_amdgcn_s_barrier()
; #define PG8_SCHED __builtin_amdgcn_sched_barrier(0)
; template <class Epi, bool ALIGN_EPI = true, bool FP8 = false>
; __device__ __forceinline__ void gemm_phase(LAS unsigned char* lds, const Gemm g, const StaticOrder& S, const Epi& E, const int wid) {
;     ...
;             const char* a1 = cA + (size_t)(t + 1) * kstep;
;             const char* a2 = last ? nA : cA + (size_t)(t + 2) * kstep; const char* b2 = last ? nB : cB + (size_t)(t + 2) * kstep;
;             const char* a3 = a2 + kstep; const char* b3 = b2 + kstep;
;             PG8_LDB(B0, 0, 0); PG8_LDB(B1, 0, 1); PG8_SCHED; PG8_LDA(At, 0, 0); PG8_STAGE(PG8_SA(1, 1), a1 + hstep, voffA);
;             PG8_WAIT_V(8); PG8_WAIT_L(0); PG8_BAR; PG8_MMA(0, 0, At, B0); PG8_MMA(0, 1, At, B1); PG8_BAR; PG8_SCHED;
;             PG8_LDA(At, 0, 1); PG8_STAGE(PG8_SB(0, 0), b2, voffB); PG8_STAGE(PG8_SB(0, 1), b2 + hstep, voffB); PG8_STAGE(PG8_SA(0, 0), a2, voffA);
;             PG8_WAIT_V(8); PG8_WAIT_L(0); PG8_BAR; PG8_MMA(1, 0, At, B0); PG8_MMA(1, 1, At, B1); PG8_BAR; PG8_SCHED;
.LBB0_2290:
	ds_read_b128 v[152:155], v218
	ds_read_b128 v[156:159], v218 offset:1024
	ds_read_b128 v[144:147], v218 offset:2048
	ds_read_b128 v[148:151], v218 offset:3072
	ds_read_b128 v[136:139], v219
	ds_read_b128 v[140:143], v219 offset:1024
	ds_read_b128 v[128:131], v219 offset:2048
	ds_read_b128 v[132:135], v219 offset:3072
	s_add_i32 s3, s38, 2
	s_add_u32 s36, s34, 0xfffc0080
	s_addc_u32 s37, s35, -1
	s_cmp_eq_u32 s88, s38
	s_cselect_b32 s38, s31, s36
	s_cselect_b32 s39, s21, s37
	s_cselect_b32 s37, s19, s90
	s_cselect_b32 s36, s87, s89
	v_lshl_add_u64 v[212:213], s[34:35], 0, v[198:199]
	s_add_i32 m0, s27, 0xc000
	ds_read_b128 v[160:163], v220
	ds_read_b128 v[164:167], v220 offset:1024
	ds_read_b128 v[168:171], v220 offset:2048
	ds_read_b128 v[172:175], v220 offset:3072
	ds_read_b128 v[176:179], v220 offset:4096
	ds_read_b128 v[180:183], v220 offset:5120
	ds_read_b128 v[204:207], v220 offset:6144
	ds_read_b128 v[208:211], v220 offset:7168
	global_load_lds_dwordx4 v[212:213], off
	v_lshl_add_u64 v[212:213], s[34:35], 0, v[200:201]
	s_add_i32 m0, s27, 0xe000
	s_nop 0
	global_load_lds_dwordx4 v[212:213], off
	s_setprio 1
	s_waitcnt vmcnt(8) lgkmcnt(0)
	s_barrier
	v_mfma_f32_16x16x128_f8f6f4 v[120:123], v[152:159], v[160:167], v[120:123]
	v_mfma_f32_16x16x128_f8f6f4 v[124:127], v[144:151], v[160:167], v[124:127]
	v_mfma_f32_16x16x128_f8f6f4 v[104:107], v[152:159], v[168:175], v[104:107]
	v_mfma_f32_16x16x128_f8f6f4 v[108:111], v[144:151], v[168:175], v[108:111]
	v_mfma_f32_16x16x128_f8f6f4 v[96:99], v[152:159], v[176:183], v[96:99]
	v_mfma_f32_16x16x128_f8f6f4 v[100:103], v[144:151], v[176:183], v[100:103]
	v_mfma_f32_16x16x128_f8f6f4 v[80:83], v[152:159], v[204:211], v[80:83]
	v_mfma_f32_16x16x128_f8f6f4 v[84:87], v[144:151], v[204:211], v[84:87]
	v_mfma_f32_16x16x128_f8f6f4 v[112:115], v[136:143], v[160:167], v[112:115]
	v_mfma_f32_16x16x128_f8f6f4 v[116:119], v[128:135], v[160:167], v[116:119]
	v_mfma_f32_16x16x128_f8f6f4 v[88:91], v[136:143], v[168:175], v[88:91]
	v_mfma_f32_16x16x128_f8f6f4 v[92:95], v[128:135], v[168:175], v[92:95]
	v_mfma_f32_16x16x128_f8f6f4 v[72:75], v[136:143], v[176:183], v[72:75]
	v_mfma_f32_16x16x128_f8f6f4 v[76:79], v[128:135], v[176:183], v[76:79]
	v_mfma_f32_16x16x128_f8f6f4 v[64:67], v[136:143], v[204:211], v[64:67]
	v_mfma_f32_16x16x128_f8f6f4 v[68:71], v[128:135], v[204:211], v[68:71]
	s_barrier
	s_setprio 0
	s_add_i32 s42, s75, s53
	v_lshl_add_u64 v[160:161], s[36:37], 0, v[188:189]
	s_mov_b32 m0, s42
	s_nop 0
	global_load_lds_dwordx4 v[160:161], off
	s_add_i32 m0, s42, 0x2000
	s_add_u32 s42, s36, 0x40000
	v_lshl_add_u64 v[162:163], s[36:37], 0, v[184:185]
	s_addc_u32 s43, s37, 0
	s_add_i32 s52, s76, s53
	global_load_lds_dwordx4 v[162:163], off
	v_lshl_add_u64 v[164:165], s[42:43], 0, v[188:189]
	s_mov_b32 m0, s52
	v_lshl_add_u64 v[166:167], s[38:39], 0, v[186:187]
	global_load_lds_dwordx4 v[164:165], off
	v_lshl_add_u64 v[164:165], s[42:43], 0, v[184:185]
	s_add_i32 m0, s52, 0x2000
	s_nop 0
	global_load_lds_dwordx4 v[164:165], off
	v_lshl_add_u64 v[164:165], s[38:39], 0, v[190:191]
	s_mov_b32 m0, s27
	s_nop 0
	global_load_lds_dwordx4 v[164:165], off
	s_mov_b32 m0, s55
	s_nop 0
	global_load_lds_dwordx4 v[166:167], off
	ds_read_b128 v[168:171], v220 offset:16384
	ds_read_b128 v[172:175], v220 offset:17408
	ds_read_b128 v[176:179], v220 offset:18432
	ds_read_b128 v[180:183], v220 offset:19456
	ds_read_b128 v[204:207], v220 offset:20480
	ds_read_b128 v[208:211], v220 offset:21504
	ds_read_b128 v[222:225], v220 offset:22528
	ds_read_b128 v[226:229], v220 offset:23552
	s_setprio 1
	s_waitcnt vmcnt(8) lgkmcnt(0)
	s_barrier
	v_mfma_f32_16x16x128_f8f6f4 v[56:59], v[152:159], v[168:175], v[56:59]
	v_mfma_f32_16x16x128_f8f6f4 v[60:63], v[144:151], v[168:175], v[60:63]
	v_mfma_f32_16x16x128_f8f6f4 v[48:51], v[152:159], v[176:183], v[48:51]
	v_mfma_f32_16x16x128_f8f6f4 v[52:55], v[144:151], v[176:183], v[52:55]
	v_mfma_f32_16x16x128_f8f6f4 v[32:35], v[152:159], v[204:211], v[32:35]
	v_mfma_f32_16x16x128_f8f6f4 v[212:215], v[144:151], v[204:211], v[36:39]
	v_mfma_f32_16x16x128_f8f6f4 v[230:233], v[152:159], v[222:229], v[16:19]
	v_mfma_f32_16x16x128_f8f6f4 v[234:237], v[144:151], v[222:229], v[20:23]
	v_mfma_f32_16x16x128_f8f6f4 v[44:47], v[128:135], v[168:175], v[44:47]
	v_mfma_f32_16x16x128_f8f6f4 v[238:241], v[136:143], v[168:175], v[40:43]
	v_mfma_f32_16x16x128_f8f6f4 v[242:245], v[136:143], v[176:183], v[24:27]
	v_mfma_f32_16x16x128_f8f6f4 v[176:179], v[128:135], v[176:183], v[28:31]
	v_mfma_f32_16x16x128_f8f6f4 v[180:183], v[136:143], v[204:211], v[8:11]
	v_mfma_f32_16x16x128_f8f6f4 v[204:207], v[128:135], v[204:211], v[12:15]
	v_mfma_f32_16x16x128_f8f6f4 v[208:211], v[136:143], v[222:229], v[0:3]
	v_mfma_f32_16x16x128_f8f6f4 v[222:225], v[128:135], v[222:229], v[4:7]
	s_barrier
; #define PG8_STAGE(bufoff, gbase, voff) do { _Pragma("unroll") for (int _i = 0; _i < 2; ++_i) \
;         __builtin_amdgcn_global_load_lds((const unsigned*)((const char*)(gbase) + (voff)[_i]), (LAS unsigned*)(lds + (bufoff) + ldsw + _i * 8192), 16, 0, 0); } while (0)
; #define PG8_LDA(dst, b, h) do { _Pragma("unroll") for (int m = 0; m < 4; ++m) _Pragma("unroll") for (int k = 0; k < 2; ++k) dst[m][k] = *(const LAS bf16x8*)(lds + PG8_SA(b, h) + aoff + m * 2048 + k * KOFF); } while (0)
; #define PG8_LDB(dst, b, h) do { _Pragma("unroll") for (int n = 0; n < 2; ++n) _Pragma("unroll") for (int k = 0; k < 2; ++k) dst[n][k] = *(const LAS bf16x8*)(lds + PG8_SB(b, h) + boff + n * 2048 + k * KOFF); } while (0)
; #define PG8_WAIT_V(n) asm volatile("s_waitcnt vmcnt(" #n ")" ::: "memory")
; #define PG8_WAIT_L(n) asm volatile("s_waitcnt lgkmcnt(" #n ")" ::: "memory")
; #define PG8_BAR __builtin_amdgcn_s_barrier()
; #define PG8_SCHED __builtin_amdgcn_sched_barrier(0)
; template <class Epi, bool ALIGN_EPI = true, bool FP8 = false>
; __device__ __forceinline__ void gemm_phase(LAS unsigned char* lds, const Gemm g, const StaticOrder& S, const Epi& E, const int wid) {
;     ...
;             PG8_LDB(B0, 1, 0); PG8_LDB(B1, 1, 1); PG8_SCHED; PG8_LDA(At, 1, 0); PG8_STAGE(PG8_SA(0, 1), a2 + hstep, voffA);
;             PG8_WAIT_V(8); PG8_WAIT_L(0); PG8_BAR; PG8_MMA(0, 0, At, B0); PG8_MMA(0, 1, At, B1); PG8_BAR; PG8_SCHED;
;             PG8_LDA(At, 1, 1); PG8_STAGE(PG8_SB(1, 0), b3, voffB); PG8_STAGE(PG8_SB(1, 1), b3 + hstep, voffB); PG8_STAGE(PG8_SA(1, 0), a3, voffA);
;             PG8_WAIT_V(8); PG8_WAIT_L(0); PG8_BAR; PG8_MMA(1, 0, At, B0); PG8_MMA(1, 1, At, B1); PG8_BAR; PG8_SCHED;
	s_setprio 0
	s_add_i32 s42, 0, 0x18000
	s_add_i32 s43, 0, 0x1c000
	s_nop 0
	v_add_u32_e32 v12, s42, v217
	v_add_u32_e32 v16, s43, v217
	ds_read_b128 v[0:3], v12
	ds_read_b128 v[4:7], v12 offset:1024
	ds_read_b128 v[8:11], v12 offset:2048
	ds_read_b128 v[12:15], v12 offset:3072
	ds_read_b128 v[128:131], v16
	ds_read_b128 v[132:135], v16 offset:1024
	ds_read_b128 v[136:139], v16 offset:2048
	ds_read_b128 v[140:143], v16 offset:3072
	s_add_u32 s38, s38, 0x40000
	s_addc_u32 s39, s39, 0
	s_mov_b32 m0, s64
	v_lshl_add_u64 v[152:153], s[38:39], 0, v[190:191]
	ds_read_b128 v[16:19], v220 offset:32768
	ds_read_b128 v[20:23], v220 offset:33792
	ds_read_b128 v[24:27], v220 offset:34816
	ds_read_b128 v[28:31], v220 offset:35840
	ds_read_b128 v[36:39], v220 offset:36864
	ds_read_b128 v[40:43], v220 offset:37888
	ds_read_b128 v[144:147], v220 offset:38912
	ds_read_b128 v[148:151], v220 offset:39936
	global_load_lds_dwordx4 v[152:153], off
	v_lshl_add_u64 v[152:153], s[38:39], 0, v[186:187]
	s_mov_b32 m0, s65
	s_nop 0
	global_load_lds_dwordx4 v[152:153], off
	s_setprio 1
	s_waitcnt vmcnt(8) lgkmcnt(0)
	s_barrier
	v_mfma_f32_16x16x128_f8f6f4 v[120:123], v[0:7], v[16:23], v[120:123]
	v_mfma_f32_16x16x128_f8f6f4 v[124:127], v[8:15], v[16:23], v[124:127]
	v_mfma_f32_16x16x128_f8f6f4 v[104:107], v[0:7], v[24:31], v[104:107]
	v_mfma_f32_16x16x128_f8f6f4 v[108:111], v[8:15], v[24:31], v[108:111]
	v_mfma_f32_16x16x128_f8f6f4 v[96:99], v[0:7], v[36:43], v[96:99]
	v_mfma_f32_16x16x128_f8f6f4 v[100:103], v[8:15], v[36:43], v[100:103]
	v_mfma_f32_16x16x128_f8f6f4 v[80:83], v[0:7], v[144:151], v[80:83]
	v_mfma_f32_16x16x128_f8f6f4 v[84:87], v[8:15], v[144:151], v[84:87]
	v_mfma_f32_16x16x128_f8f6f4 v[112:115], v[128:135], v[16:23], v[112:115]
	v_mfma_f32_16x16x128_f8f6f4 v[116:119], v[136:143], v[16:23], v[116:119]
	v_mfma_f32_16x16x128_f8f6f4 v[88:91], v[128:135], v[24:31], v[88:91]
	v_mfma_f32_16x16x128_f8f6f4 v[92:95], v[136:143], v[24:31], v[92:95]
	v_mfma_f32_16x16x128_f8f6f4 v[72:75], v[128:135], v[36:43], v[72:75]
	v_mfma_f32_16x16x128_f8f6f4 v[76:79], v[136:143], v[36:43], v[76:79]
	v_mfma_f32_16x16x128_f8f6f4 v[64:67], v[128:135], v[144:151], v[64:67]
	v_mfma_f32_16x16x128_f8f6f4 v[68:71], v[136:143], v[144:151], v[68:71]
	s_barrier
	s_setprio 0
	s_add_i32 s38, s42, s53
	v_lshl_add_u64 v[16:17], v[160:161], 0, s[14:15]
	s_mov_b32 m0, s38
	s_nop 0
	global_load_lds_dwordx4 v[16:17], off
	s_add_i32 m0, s38, 0x2000
	s_add_u32 s36, s36, 0x40080
	v_lshl_add_u64 v[16:17], v[162:163], 0, s[14:15]
	s_addc_u32 s37, s37, 0
	s_add_i32 s38, s43, s53
	global_load_lds_dwordx4 v[16:17], off
	v_lshl_add_u64 v[16:17], s[36:37], 0, v[188:189]
	s_mov_b32 m0, s38
	s_nop 0
	global_load_lds_dwordx4 v[16:17], off
	v_lshl_add_u64 v[16:17], s[36:37], 0, v[184:185]
	s_add_i32 m0, s38, 0x2000
	s_nop 0
	global_load_lds_dwordx4 v[16:17], off
	v_lshl_add_u64 v[16:17], v[164:165], 0, s[14:15]
	s_mov_b32 m0, s71
	s_nop 0
	global_load_lds_dwordx4 v[16:17], off
	v_lshl_add_u64 v[16:17], v[166:167], 0, s[14:15]
	s_mov_b32 m0, s72
	s_nop 0
	global_load_lds_dwordx4 v[16:17], off
	ds_read_b128 v[24:27], v220 offset:49152
	ds_read_b128 v[28:31], v220 offset:50176
	ds_read_b128 v[144:147], v220 offset:51200
	ds_read_b128 v[148:151], v220 offset:52224
	ds_read_b128 v[152:155], v220 offset:53248
	ds_read_b128 v[156:159], v220 offset:54272
	ds_read_b128 v[168:171], v220 offset:55296
	ds_read_b128 v[172:175], v220 offset:56320
	s_setprio 1
	s_waitcnt vmcnt(8) lgkmcnt(0)
	s_barrier
	v_mfma_f32_16x16x128_f8f6f4 v[56:59], v[0:7], v[24:31], v[56:59]
	v_mfma_f32_16x16x128_f8f6f4 v[60:63], v[8:15], v[24:31], v[60:63]
	v_mfma_f32_16x16x128_f8f6f4 v[48:51], v[0:7], v[144:151], v[48:51]
	v_mfma_f32_16x16x128_f8f6f4 v[52:55], v[8:15], v[144:151], v[52:55]
	v_mfma_f32_16x16x128_f8f6f4 v[32:35], v[0:7], v[152:159], v[32:35]
	v_mfma_f32_16x16x128_f8f6f4 v[36:39], v[8:15], v[152:159], v[212:215]
	v_mfma_f32_16x16x128_f8f6f4 v[16:19], v[0:7], v[168:175], v[230:233]
	v_mfma_f32_16x16x128_f8f6f4 v[20:23], v[8:15], v[168:175], v[234:237]
	v_mfma_f32_16x16x128_f8f6f4 v[40:43], v[128:135], v[24:31], v[238:241]
	v_mfma_f32_16x16x128_f8f6f4 v[44:47], v[136:143], v[24:31], v[44:47]
	v_mfma_f32_16x16x128_f8f6f4 v[24:27], v[128:135], v[144:151], v[242:245]
	v_mfma_f32_16x16x128_f8f6f4 v[28:31], v[136:143], v[144:151], v[176:179]
	v_mfma_f32_16x16x128_f8f6f4 v[8:11], v[128:135], v[152:159], v[180:183]
	v_mfma_f32_16x16x128_f8f6f4 v[12:15], v[136:143], v[152:159], v[204:207]
	v_mfma_f32_16x16x128_f8f6f4 v[0:3], v[128:135], v[168:175], v[208:211]
	v_mfma_f32_16x16x128_f8f6f4 v[4:7], v[136:143], v[168:175], v[222:225]
	s_barrier
	s_setprio 0
	s_add_u32 s34, s34, 0x100
	s_addc_u32 s35, s35, 0
	s_add_u32 s89, s89, 0x100
	s_addc_u32 s90, s90, 0
	s_cmp_ge_u32 s3, s29
	s_mov_b32 s38, s3
	s_cbranch_scc0 .LBB0_2290
	s_and_b64 vcc, exec, s[12:13]
	s_cbranch_vccz .LBB0_2293
	s_barrier

; #define PG8_STAGE(bufoff, gbase, voff) do { _Pragma("unroll") for (int _i = 0; _i < 2; ++_i) \
;         __builtin_amdgcn_global_load_lds((const unsigned*)((const char*)(gbase) + (voff)[_i]), (LAS unsigned*)(lds + (bufoff) + ldsw + _i * 8192), 16, 0, 0); } while (0)
; #define PG8_LDA(dst, b, h) do { _Pragma("unroll") for (int m = 0; m < 4; ++m) _Pragma("unroll") for (int k = 0; k < 2; ++k) dst[m][k] = *(const LAS bf16x8*)(lds + PG8_SA(b, h) + aoff + m * 2048 + k * KOFF); } while (0)
; #define PG8_LDB(dst, b, h) do { _Pragma("unroll") for (int n = 0; n < 2; ++n) _Pragma("unroll") for (int k = 0; k < 2; ++k) dst[n][k] = *(const LAS bf16x8*)(lds + PG8_SB(b, h) + boff + n * 2048 + k * KOFF); } while (0)
; #define PG8_WAIT_V(n) asm volatile("s_waitcnt vmcnt(" #n ")" ::: "memory")
; #define PG8_WAIT_L(n) asm volatile("s_waitcnt lgkmcnt(" #n ")" ::: "memory")
; #define PG8_BAR __builtin_amdgcn_s_barrier()
; #define PG8_SCHED __builtin_amdgcn_sched_barrier(0)
; template <class Epi, bool ALIGN_EPI = true, bool FP8 = false>
; __device__ __forceinline__ void gemm_phase(LAS unsigned char* lds, const Gemm g, const StaticOrder& S, const Epi& E, const int wid) {
;     ...
;             const char* a1 = cA + (size_t)(t + 1) * kstep;
;             const char* a2 = last ? nA : cA + (size_t)(t + 2) * kstep; const char* b2 = last ? nB : cB + (size_t)(t + 2) * kstep;
;             const char* a3 = a2 + kstep; const char* b3 = b2 + kstep;
;             PG8_LDB(B0, 0, 0); PG8_LDB(B1, 0, 1); PG8_SCHED; PG8_LDA(At, 0, 0); PG8_STAGE(PG8_SA(1, 1), a1 + hstep, voffA);
;             PG8_WAIT_V(8); PG8_WAIT_L(0); PG8_BAR; PG8_MMA(0, 0, At, B0); PG8_MMA(0, 1, At, B1); PG8_BAR; PG8_SCHED;
;             PG8_LDA(At, 0, 1); PG8_STAGE(PG8_SB(0, 0), b2, voffB); PG8_STAGE(PG8_SB(0, 1), b2 + hstep, voffB); PG8_STAGE(PG8_SA(0, 0), a2, voffA);
;             PG8_WAIT_V(8); PG8_WAIT_L(0); PG8_BAR; PG8_MMA(1, 0, At, B0); PG8_MMA(1, 1, At, B1); PG8_BAR; PG8_SCHED;
.LBB0_2452:
	ds_read_b128 v[152:155], v148
	ds_read_b128 v[156:159], v148 offset:1024
	ds_read_b128 v[160:163], v148 offset:2048
	ds_read_b128 v[164:167], v148 offset:3072
	ds_read_b128 v[168:171], v149
	ds_read_b128 v[172:175], v149 offset:1024
	ds_read_b128 v[176:179], v149 offset:2048
	ds_read_b128 v[180:183], v149 offset:3072
	s_add_i32 s76, s30, 2
	s_add_u32 s31, s28, 0xfff80080
	s_addc_u32 s34, s29, -1
	s_cmp_eq_u32 s43, s30
	s_cselect_b32 s30, s42, s52
	s_cselect_b32 s35, s3, s34
	s_cselect_b32 s34, s17, s31
	s_cselect_b32 s31, s19, s75
	v_lshl_add_u64 v[144:145], s[28:29], 0, v[138:139]
	s_add_i32 m0, s25, 0xc000
	ds_read_b128 v[184:187], v150
	ds_read_b128 v[188:191], v150 offset:1024
	ds_read_b128 v[192:195], v150 offset:2048
	ds_read_b128 v[196:199], v150 offset:3072
	ds_read_b128 v[200:203], v150 offset:4096
	ds_read_b128 v[204:207], v150 offset:5120
	ds_read_b128 v[208:211], v150 offset:6144
	ds_read_b128 v[212:215], v150 offset:7168
	global_load_lds_dwordx4 v[144:145], off
	v_lshl_add_u64 v[144:145], s[28:29], 0, v[140:141]
	s_add_i32 m0, s25, 0xe000
	s_nop 0
	global_load_lds_dwordx4 v[144:145], off
	s_setprio 1
	s_waitcnt vmcnt(8) lgkmcnt(0)
	s_barrier
	v_mfma_f32_16x16x32_bf16 v[124:127], v[152:155], v[184:187], v[124:127]
	v_mfma_f32_16x16x32_bf16 v[116:119], v[160:163], v[184:187], v[116:119]
	v_mfma_f32_16x16x32_bf16 v[108:111], v[152:155], v[192:195], v[108:111]
	v_mfma_f32_16x16x32_bf16 v[100:103], v[160:163], v[192:195], v[100:103]
	v_mfma_f32_16x16x32_bf16 v[92:95], v[152:155], v[200:203], v[92:95]
	v_mfma_f32_16x16x32_bf16 v[84:87], v[160:163], v[200:203], v[84:87]
	v_mfma_f32_16x16x32_bf16 v[76:79], v[152:155], v[208:211], v[76:79]
	v_mfma_f32_16x16x32_bf16 v[68:71], v[160:163], v[208:211], v[68:71]
	v_mfma_f32_16x16x32_bf16 v[124:127], v[156:159], v[188:191], v[124:127]
	v_mfma_f32_16x16x32_bf16 v[116:119], v[164:167], v[188:191], v[116:119]
	v_mfma_f32_16x16x32_bf16 v[108:111], v[156:159], v[196:199], v[108:111]
	v_mfma_f32_16x16x32_bf16 v[100:103], v[164:167], v[196:199], v[100:103]
	v_mfma_f32_16x16x32_bf16 v[92:95], v[156:159], v[204:207], v[92:95]
	v_mfma_f32_16x16x32_bf16 v[84:87], v[164:167], v[204:207], v[84:87]
	v_mfma_f32_16x16x32_bf16 v[76:79], v[156:159], v[212:215], v[76:79]
	v_mfma_f32_16x16x32_bf16 v[68:71], v[164:167], v[212:215], v[68:71]
	v_mfma_f32_16x16x32_bf16 v[120:123], v[168:171], v[184:187], v[120:123]
	v_mfma_f32_16x16x32_bf16 v[112:115], v[176:179], v[184:187], v[112:115]
	v_mfma_f32_16x16x32_bf16 v[104:107], v[168:171], v[192:195], v[104:107]
	v_mfma_f32_16x16x32_bf16 v[96:99], v[176:179], v[192:195], v[96:99]
	v_mfma_f32_16x16x32_bf16 v[88:91], v[168:171], v[200:203], v[88:91]
	v_mfma_f32_16x16x32_bf16 v[80:83], v[176:179], v[200:203], v[80:83]
	v_mfma_f32_16x16x32_bf16 v[72:75], v[168:171], v[208:211], v[72:75]
	v_mfma_f32_16x16x32_bf16 v[64:67], v[176:179], v[208:211], v[64:67]
	v_mfma_f32_16x16x32_bf16 v[120:123], v[172:175], v[188:191], v[120:123]
	v_mfma_f32_16x16x32_bf16 v[112:115], v[180:183], v[188:191], v[112:115]
	v_mfma_f32_16x16x32_bf16 v[104:107], v[172:175], v[196:199], v[104:107]
	v_mfma_f32_16x16x32_bf16 v[96:99], v[180:183], v[196:199], v[96:99]
	v_mfma_f32_16x16x32_bf16 v[88:91], v[172:175], v[204:207], v[88:91]
	v_mfma_f32_16x16x32_bf16 v[80:83], v[180:183], v[204:207], v[80:83]
	v_mfma_f32_16x16x32_bf16 v[72:75], v[172:175], v[212:215], v[72:75]
	v_mfma_f32_16x16x32_bf16 v[64:67], v[180:183], v[212:215], v[64:67]
	s_barrier
	s_setprio 0
	s_add_i32 s77, s65, s38
	v_lshl_add_u64 v[144:145], s[30:31], 0, v[132:133]
	s_mov_b32 m0, s77
	s_nop 0
	global_load_lds_dwordx4 v[144:145], off
	s_add_i32 m0, s77, 0x2000
	s_add_u32 s78, s30, 0x80000
	v_lshl_add_u64 v[216:217], s[30:31], 0, v[128:129]
	s_addc_u32 s79, s31, 0
	s_add_i32 s77, s66, s38
	global_load_lds_dwordx4 v[216:217], off
	v_lshl_add_u64 v[218:219], s[78:79], 0, v[132:133]
	s_mov_b32 m0, s77
	v_lshl_add_u64 v[220:221], s[34:35], 0, v[130:131]
	global_load_lds_dwordx4 v[218:219], off
	v_lshl_add_u64 v[218:219], s[78:79], 0, v[128:129]
	s_add_i32 m0, s77, 0x2000
	s_nop 0
	global_load_lds_dwordx4 v[218:219], off
	v_lshl_add_u64 v[218:219], s[34:35], 0, v[134:135]
	s_mov_b32 m0, s25
	s_nop 0
	global_load_lds_dwordx4 v[218:219], off
	s_mov_b32 m0, s27
	s_nop 0
	global_load_lds_dwordx4 v[220:221], off
	ds_read_b128 v[184:187], v150 offset:16384
	ds_read_b128 v[188:191], v150 offset:17408
	ds_read_b128 v[192:195], v150 offset:18432
	ds_read_b128 v[196:199], v150 offset:19456
	ds_read_b128 v[200:203], v150 offset:20480
	ds_read_b128 v[204:207], v150 offset:21504
	ds_read_b128 v[208:211], v150 offset:22528
	ds_read_b128 v[212:215], v150 offset:23552
	s_setprio 1
	s_waitcnt vmcnt(8) lgkmcnt(0)
	s_barrier
; #define PG8_STAGE(bufoff, gbase, voff) do { _Pragma("unroll") for (int _i = 0; _i < 2; ++_i) \
;         __builtin_amdgcn_global_load_lds((const unsigned*)((const char*)(gbase) + (voff)[_i]), (LAS unsigned*)(lds + (bufoff) + ldsw + _i * 8192), 16, 0, 0); } while (0)
; #define PG8_LDA(dst, b, h) do { _Pragma("unroll") for (int m = 0; m < 4; ++m) _Pragma("unroll") for (int k = 0; k < 2; ++k) dst[m][k] = *(const LAS bf16x8*)(lds + PG8_SA(b, h) + aoff + m * 2048 + k * KOFF); } while (0)
; #define PG8_LDB(dst, b, h) do { _Pragma("unroll") for (int n = 0; n < 2; ++n) _Pragma("unroll") for (int k = 0; k < 2; ++k) dst[n][k] = *(const LAS bf16x8*)(lds + PG8_SB(b, h) + boff + n * 2048 + k * KOFF); } while (0)
; #define PG8_WAIT_V(n) asm volatile("s_waitcnt vmcnt(" #n ")" ::: "memory")
; #define PG8_WAIT_L(n) asm volatile("s_waitcnt lgkmcnt(" #n ")" ::: "memory")
; #define PG8_BAR __builtin_amdgcn_s_barrier()
; #define PG8_SCHED __builtin_amdgcn_sched_barrier(0)
; template <class Epi, bool ALIGN_EPI = true, bool FP8 = false>
; __device__ __forceinline__ void gemm_phase(LAS unsigned char* lds, const Gemm g, const StaticOrder& S, const Epi& E, const int wid) {
;     ...
;             PG8_LDB(B0, 1, 0); PG8_LDB(B1, 1, 1); PG8_SCHED; PG8_LDA(At, 1, 0); PG8_STAGE(PG8_SA(0, 1), a2 + hstep, voffA);
;             PG8_WAIT_V(8); PG8_WAIT_L(0); PG8_BAR; PG8_MMA(0, 0, At, B0); PG8_MMA(0, 1, At, B1); PG8_BAR; PG8_SCHED;
;             PG8_LDA(At, 1, 1); PG8_STAGE(PG8_SB(1, 0), b3, voffB); PG8_STAGE(PG8_SB(1, 1), b3 + hstep, voffB); PG8_STAGE(PG8_SA(1, 0), a3, voffA);
;             PG8_WAIT_V(8); PG8_WAIT_L(0); PG8_BAR; PG8_MMA(1, 0, At, B0); PG8_MMA(1, 1, At, B1); PG8_BAR; PG8_SCHED;
	v_mfma_f32_16x16x32_bf16 v[60:63], v[152:155], v[184:187], v[60:63]
	v_mfma_f32_16x16x32_bf16 v[52:55], v[160:163], v[184:187], v[52:55]
	v_mfma_f32_16x16x32_bf16 v[44:47], v[152:155], v[192:195], v[44:47]
	v_mfma_f32_16x16x32_bf16 v[36:39], v[160:163], v[192:195], v[36:39]
	v_mfma_f32_16x16x32_bf16 v[28:31], v[152:155], v[200:203], v[28:31]
	v_mfma_f32_16x16x32_bf16 v[20:23], v[160:163], v[200:203], v[20:23]
	v_mfma_f32_16x16x32_bf16 v[12:15], v[152:155], v[208:211], v[12:15]
	v_mfma_f32_16x16x32_bf16 v[4:7], v[160:163], v[208:211], v[4:7]
	v_mfma_f32_16x16x32_bf16 v[60:63], v[156:159], v[188:191], v[60:63]
	v_mfma_f32_16x16x32_bf16 v[52:55], v[164:167], v[188:191], v[52:55]
	v_mfma_f32_16x16x32_bf16 v[44:47], v[156:159], v[196:199], v[44:47]
	v_mfma_f32_16x16x32_bf16 v[36:39], v[164:167], v[196:199], v[36:39]
	v_mfma_f32_16x16x32_bf16 v[28:31], v[156:159], v[204:207], v[28:31]
	v_mfma_f32_16x16x32_bf16 v[20:23], v[164:167], v[204:207], v[20:23]
	v_mfma_f32_16x16x32_bf16 v[12:15], v[156:159], v[212:215], v[12:15]
	v_mfma_f32_16x16x32_bf16 v[4:7], v[164:167], v[212:215], v[4:7]
	v_mfma_f32_16x16x32_bf16 v[56:59], v[168:171], v[184:187], v[56:59]
	v_mfma_f32_16x16x32_bf16 v[48:51], v[176:179], v[184:187], v[48:51]
	v_mfma_f32_16x16x32_bf16 v[40:43], v[168:171], v[192:195], v[40:43]
	v_mfma_f32_16x16x32_bf16 v[32:35], v[176:179], v[192:195], v[32:35]
	v_mfma_f32_16x16x32_bf16 v[24:27], v[168:171], v[200:203], v[24:27]
	v_mfma_f32_16x16x32_bf16 v[16:19], v[176:179], v[200:203], v[16:19]
	v_mfma_f32_16x16x32_bf16 v[8:11], v[168:171], v[208:211], v[8:11]
	v_mfma_f32_16x16x32_bf16 v[0:3], v[176:179], v[208:211], v[0:3]
	v_mfma_f32_16x16x32_bf16 v[56:59], v[172:175], v[188:191], v[56:59]
	v_mfma_f32_16x16x32_bf16 v[48:51], v[180:183], v[188:191], v[48:51]
	v_mfma_f32_16x16x32_bf16 v[40:43], v[172:175], v[196:199], v[40:43]
	v_mfma_f32_16x16x32_bf16 v[32:35], v[180:183], v[196:199], v[32:35]
	v_mfma_f32_16x16x32_bf16 v[24:27], v[172:175], v[204:207], v[24:27]
	v_mfma_f32_16x16x32_bf16 v[16:19], v[180:183], v[204:207], v[16:19]
	v_mfma_f32_16x16x32_bf16 v[8:11], v[172:175], v[212:215], v[8:11]
	v_mfma_f32_16x16x32_bf16 v[0:3], v[180:183], v[212:215], v[0:3]
	s_barrier
	s_setprio 0
	s_add_i32 s77, 0, 0x18000
	s_add_i32 s78, 0, 0x1c000
	v_add_u32_e32 v164, s77, v147
	v_add_u32_e32 v180, s78, v147
	ds_read_b128 v[152:155], v164
	ds_read_b128 v[156:159], v164 offset:1024
	ds_read_b128 v[160:163], v164 offset:2048
	ds_read_b128 v[164:167], v164 offset:3072
	ds_read_b128 v[168:171], v180
	ds_read_b128 v[172:175], v180 offset:1024
	ds_read_b128 v[176:179], v180 offset:2048
	ds_read_b128 v[180:183], v180 offset:3072
	s_add_u32 s34, s34, 0x80000
	s_addc_u32 s35, s35, 0
	s_mov_b32 m0, s39
	v_lshl_add_u64 v[222:223], s[34:35], 0, v[134:135]
	ds_read_b128 v[184:187], v150 offset:32768
	ds_read_b128 v[188:191], v150 offset:33792
	ds_read_b128 v[192:195], v150 offset:34816
	ds_read_b128 v[196:199], v150 offset:35840
	ds_read_b128 v[200:203], v150 offset:36864
	ds_read_b128 v[204:207], v150 offset:37888
	ds_read_b128 v[208:211], v150 offset:38912
	ds_read_b128 v[212:215], v150 offset:39936
	global_load_lds_dwordx4 v[222:223], off
	v_lshl_add_u64 v[222:223], s[34:35], 0, v[130:131]
	s_mov_b32 m0, s48
	s_nop 0
	global_load_lds_dwordx4 v[222:223], off
	s_setprio 1
	s_waitcnt vmcnt(8) lgkmcnt(0)
	s_barrier
	v_mfma_f32_16x16x32_bf16 v[124:127], v[152:155], v[184:187], v[124:127]
	v_mfma_f32_16x16x32_bf16 v[116:119], v[160:163], v[184:187], v[116:119]
	v_mfma_f32_16x16x32_bf16 v[108:111], v[152:155], v[192:195], v[108:111]
	v_mfma_f32_16x16x32_bf16 v[100:103], v[160:163], v[192:195], v[100:103]
	v_mfma_f32_16x16x32_bf16 v[92:95], v[152:155], v[200:203], v[92:95]
	v_mfma_f32_16x16x32_bf16 v[84:87], v[160:163], v[200:203], v[84:87]
	v_mfma_f32_16x16x32_bf16 v[76:79], v[152:155], v[208:211], v[76:79]
	v_mfma_f32_16x16x32_bf16 v[68:71], v[160:163], v[208:211], v[68:71]
	v_mfma_f32_16x16x32_bf16 v[124:127], v[156:159], v[188:191], v[124:127]
	v_mfma_f32_16x16x32_bf16 v[116:119], v[164:167], v[188:191], v[116:119]
	v_mfma_f32_16x16x32_bf16 v[108:111], v[156:159], v[196:199], v[108:111]
	v_mfma_f32_16x16x32_bf16 v[100:103], v[164:167], v[196:199], v[100:103]
	v_mfma_f32_16x16x32_bf16 v[92:95], v[156:159], v[204:207], v[92:95]
	v_mfma_f32_16x16x32_bf16 v[84:87], v[164:167], v[204:207], v[84:87]
	v_mfma_f32_16x16x32_bf16 v[76:79], v[156:159], v[212:215], v[76:79]
	v_mfma_f32_16x16x32_bf16 v[68:71], v[164:167], v[212:215], v[68:71]
	v_mfma_f32_16x16x32_bf16 v[120:123], v[168:171], v[184:187], v[120:123]
	v_mfma_f32_16x16x32_bf16 v[112:115], v[176:179], v[184:187], v[112:115]
	v_mfma_f32_16x16x32_bf16 v[104:107], v[168:171], v[192:195], v[104:107]
	v_mfma_f32_16x16x32_bf16 v[96:99], v[176:179], v[192:195], v[96:99]
	v_mfma_f32_16x16x32_bf16 v[88:91], v[168:171], v[200:203], v[88:91]
	v_mfma_f32_16x16x32_bf16 v[80:83], v[176:179], v[200:203], v[80:83]
	v_mfma_f32_16x16x32_bf16 v[72:75], v[168:171], v[208:211], v[72:75]
	v_mfma_f32_16x16x32_bf16 v[64:67], v[176:179], v[208:211], v[64:67]
	v_mfma_f32_16x16x32_bf16 v[120:123], v[172:175], v[188:191], v[120:123]
	v_mfma_f32_16x16x32_bf16 v[112:115], v[180:183], v[188:191], v[112:115]
	v_mfma_f32_16x16x32_bf16 v[104:107], v[172:175], v[196:199], v[104:107]
	v_mfma_f32_16x16x32_bf16 v[96:99], v[180:183], v[196:199], v[96:99]
	v_mfma_f32_16x16x32_bf16 v[88:91], v[172:175], v[204:207], v[88:91]
	v_mfma_f32_16x16x32_bf16 v[80:83], v[180:183], v[204:207], v[80:83]
	v_mfma_f32_16x16x32_bf16 v[72:75], v[172:175], v[212:215], v[72:75]
	v_mfma_f32_16x16x32_bf16 v[64:67], v[180:183], v[212:215], v[64:67]
	s_barrier
; #define PG8_STAGE(bufoff, gbase, voff) do { _Pragma("unroll") for (int _i = 0; _i < 2; ++_i) \
;         __builtin_amdgcn_global_load_lds((const unsigned*)((const char*)(gbase) + (voff)[_i]), (LAS unsigned*)(lds + (bufoff) + ldsw + _i * 8192), 16, 0, 0); } while (0)
; #define PG8_LDA(dst, b, h) do { _Pragma("unroll") for (int m = 0; m < 4; ++m) _Pragma("unroll") for (int k = 0; k < 2; ++k) dst[m][k] = *(const LAS bf16x8*)(lds + PG8_SA(b, h) + aoff + m * 2048 + k * KOFF); } while (0)
; #define PG8_WAIT_V(n) asm volatile("s_waitcnt vmcnt(" #n ")" ::: "memory")
; #define PG8_WAIT_L(n) asm volatile("s_waitcnt lgkmcnt(" #n ")" ::: "memory")
; #define PG8_BAR __builtin_amdgcn_s_barrier()
; #define PG8_SCHED __builtin_amdgcn_sched_barrier(0)
; template <class Epi, bool ALIGN_EPI = true, bool FP8 = false>
; __device__ __forceinline__ void gemm_phase(LAS unsigned char* lds, const Gemm g, const StaticOrder& S, const Epi& E, const int wid) {
;     ...
;             PG8_LDA(At, 1, 1); PG8_STAGE(PG8_SB(1, 0), b3, voffB); PG8_STAGE(PG8_SB(1, 1), b3 + hstep, voffB); PG8_STAGE(PG8_SA(1, 0), a3, voffA);
;             PG8_WAIT_V(8); PG8_WAIT_L(0); PG8_BAR; PG8_MMA(1, 0, At, B0); PG8_MMA(1, 1, At, B1); PG8_BAR; PG8_SCHED;
;         }
	s_setprio 0
	s_add_i32 s34, s77, s38
	v_lshl_add_u64 v[144:145], v[144:145], 0, s[14:15]
	s_mov_b32 m0, s34
	s_nop 0
	global_load_lds_dwordx4 v[144:145], off
	s_add_i32 m0, s34, 0x2000
	s_add_u32 s30, s30, 0x80080
	v_lshl_add_u64 v[144:145], v[216:217], 0, s[14:15]
	s_addc_u32 s31, s31, 0
	s_add_i32 s34, s78, s38
	global_load_lds_dwordx4 v[144:145], off
	v_lshl_add_u64 v[144:145], s[30:31], 0, v[132:133]
	s_mov_b32 m0, s34
	s_nop 0
	global_load_lds_dwordx4 v[144:145], off
	v_lshl_add_u64 v[144:145], s[30:31], 0, v[128:129]
	s_add_i32 m0, s34, 0x2000
	s_nop 0
	global_load_lds_dwordx4 v[144:145], off
	v_lshl_add_u64 v[144:145], v[218:219], 0, s[14:15]
	s_mov_b32 m0, s53
	s_nop 0
	global_load_lds_dwordx4 v[144:145], off
	v_lshl_add_u64 v[144:145], v[220:221], 0, s[14:15]
	s_mov_b32 m0, s55
	s_nop 0
	global_load_lds_dwordx4 v[144:145], off
	ds_read_b128 v[184:187], v150 offset:49152
	ds_read_b128 v[188:191], v150 offset:50176
	ds_read_b128 v[192:195], v150 offset:51200
	ds_read_b128 v[196:199], v150 offset:52224
	ds_read_b128 v[200:203], v150 offset:53248
	ds_read_b128 v[204:207], v150 offset:54272
	ds_read_b128 v[208:211], v150 offset:55296
	ds_read_b128 v[212:215], v150 offset:56320
	s_setprio 1
	s_waitcnt vmcnt(8) lgkmcnt(0)
	s_barrier
	v_mfma_f32_16x16x32_bf16 v[60:63], v[152:155], v[184:187], v[60:63]
	v_mfma_f32_16x16x32_bf16 v[52:55], v[160:163], v[184:187], v[52:55]
	v_mfma_f32_16x16x32_bf16 v[44:47], v[152:155], v[192:195], v[44:47]
	v_mfma_f32_16x16x32_bf16 v[36:39], v[160:163], v[192:195], v[36:39]
	v_mfma_f32_16x16x32_bf16 v[28:31], v[152:155], v[200:203], v[28:31]
	v_mfma_f32_16x16x32_bf16 v[20:23], v[160:163], v[200:203], v[20:23]
	v_mfma_f32_16x16x32_bf16 v[12:15], v[152:155], v[208:211], v[12:15]
	v_mfma_f32_16x16x32_bf16 v[4:7], v[160:163], v[208:211], v[4:7]
	v_mfma_f32_16x16x32_bf16 v[60:63], v[156:159], v[188:191], v[60:63]
	v_mfma_f32_16x16x32_bf16 v[52:55], v[164:167], v[188:191], v[52:55]
	v_mfma_f32_16x16x32_bf16 v[44:47], v[156:159], v[196:199], v[44:47]
	v_mfma_f32_16x16x32_bf16 v[36:39], v[164:167], v[196:199], v[36:39]
	v_mfma_f32_16x16x32_bf16 v[28:31], v[156:159], v[204:207], v[28:31]
	v_mfma_f32_16x16x32_bf16 v[20:23], v[164:167], v[204:207], v[20:23]
	v_mfma_f32_16x16x32_bf16 v[12:15], v[156:159], v[212:215], v[12:15]
	v_mfma_f32_16x16x32_bf16 v[4:7], v[164:167], v[212:215], v[4:7]
	v_mfma_f32_16x16x32_bf16 v[56:59], v[168:171], v[184:187], v[56:59]
	v_mfma_f32_16x16x32_bf16 v[48:51], v[176:179], v[184:187], v[48:51]
	v_mfma_f32_16x16x32_bf16 v[40:43], v[168:171], v[192:195], v[40:43]
	v_mfma_f32_16x16x32_bf16 v[32:35], v[176:179], v[192:195], v[32:35]
	v_mfma_f32_16x16x32_bf16 v[24:27], v[168:171], v[200:203], v[24:27]
	v_mfma_f32_16x16x32_bf16 v[16:19], v[176:179], v[200:203], v[16:19]
	v_mfma_f32_16x16x32_bf16 v[8:11], v[168:171], v[208:211], v[8:11]
	v_mfma_f32_16x16x32_bf16 v[0:3], v[176:179], v[208:211], v[0:3]
	v_mfma_f32_16x16x32_bf16 v[56:59], v[172:175], v[188:191], v[56:59]
	v_mfma_f32_16x16x32_bf16 v[48:51], v[180:183], v[188:191], v[48:51]
	v_mfma_f32_16x16x32_bf16 v[40:43], v[172:175], v[196:199], v[40:43]
	v_mfma_f32_16x16x32_bf16 v[32:35], v[180:183], v[196:199], v[32:35]
	v_mfma_f32_16x16x32_bf16 v[24:27], v[172:175], v[204:207], v[24:27]
	v_mfma_f32_16x16x32_bf16 v[16:19], v[180:183], v[204:207], v[16:19]
	v_mfma_f32_16x16x32_bf16 v[8:11], v[172:175], v[212:215], v[8:11]
	v_mfma_f32_16x16x32_bf16 v[0:3], v[180:183], v[212:215], v[0:3]
	s_barrier
	s_setprio 0
	s_add_u32 s28, s28, 0x100
	s_addc_u32 s29, s29, 0
	s_add_u32 s52, s52, 0x100
	s_addc_u32 s75, s75, 0
	s_cmp_ge_u32 s76, s54
	s_mov_b32 s30, s76
	s_cbranch_scc0 .LBB0_2452
	s_and_b64 vcc, exec, s[12:13]
	s_cbranch_vccz .LBB0_2455

; #define PG8_STAGE(bufoff, gbase, voff) do { _Pragma("unroll") for (int _i = 0; _i < 2; ++_i) \
;         __builtin_amdgcn_global_load_lds((const unsigned*)((const char*)(gbase) + (voff)[_i]), (LAS unsigned*)(lds + (bufoff) + ldsw + _i * 8192), 16, 0, 0); } while (0)
; #define PG8_LDA(dst, b, h) do { _Pragma("unroll") for (int m = 0; m < 4; ++m) _Pragma("unroll") for (int k = 0; k < 2; ++k) dst[m][k] = *(const LAS bf16x8*)(lds + PG8_SA(b, h) + aoff + m * 2048 + k * KOFF); } while (0)
; #define PG8_LDB(dst, b, h) do { _Pragma("unroll") for (int n = 0; n < 2; ++n) _Pragma("unroll") for (int k = 0; k < 2; ++k) dst[n][k] = *(const LAS bf16x8*)(lds + PG8_SB(b, h) + boff + n * 2048 + k * KOFF); } while (0)
; #define PG8_WAIT_V(n) asm volatile("s_waitcnt vmcnt(" #n ")" ::: "memory")
; #define PG8_WAIT_L(n) asm volatile("s_waitcnt lgkmcnt(" #n ")" ::: "memory")
; #define PG8_BAR __builtin_amdgcn_s_barrier()
; #define PG8_SCHED __builtin_amdgcn_sched_barrier(0)
; template <class Epi, bool ALIGN_EPI = true, bool FP8 = false>
; __device__ __forceinline__ void gemm_phase(LAS unsigned char* lds, const Gemm g, const StaticOrder& S, const Epi& E, const int wid) {
;     ...
;             const char* a1 = cA + (size_t)(t + 1) * kstep;
;             const char* a2 = last ? nA : cA + (size_t)(t + 2) * kstep; const char* b2 = last ? nB : cB + (size_t)(t + 2) * kstep;
;             const char* a3 = a2 + kstep; const char* b3 = b2 + kstep;
;             PG8_LDB(B0, 0, 0); PG8_LDB(B1, 0, 1); PG8_SCHED; PG8_LDA(At, 0, 0); PG8_STAGE(PG8_SA(1, 1), a1 + hstep, voffA);
;             PG8_WAIT_V(8); PG8_WAIT_L(0); PG8_BAR; PG8_MMA(0, 0, At, B0); PG8_MMA(0, 1, At, B1); PG8_BAR; PG8_SCHED;
;             PG8_LDA(At, 0, 1); PG8_STAGE(PG8_SB(0, 0), b2, voffB); PG8_STAGE(PG8_SB(0, 1), b2 + hstep, voffB); PG8_STAGE(PG8_SA(0, 0), a2, voffA);
;             PG8_WAIT_V(8); PG8_WAIT_L(0); PG8_BAR; PG8_MMA(1, 0, At, B0); PG8_MMA(1, 1, At, B1); PG8_BAR; PG8_SCHED;
.LBB0_2536:
	ds_read_b128 v[152:155], v188
	ds_read_b128 v[156:159], v188 offset:1024
	ds_read_b128 v[144:147], v188 offset:2048
	ds_read_b128 v[148:151], v188 offset:3072
	ds_read_b128 v[136:139], v189
	ds_read_b128 v[140:143], v189 offset:1024
	ds_read_b128 v[128:131], v189 offset:2048
	ds_read_b128 v[132:135], v189 offset:3072
	s_add_i32 s42, s26, 2
	s_add_u32 s27, s24, 0xfff50080
	s_addc_u32 s28, s25, -1
	s_cmp_eq_u32 s81, s26
	s_cselect_b32 s26, s20, s82
	s_cselect_b32 s29, s7, s28
	s_cselect_b32 s28, s6, s27
	s_cselect_b32 s27, s21, s83
	v_lshl_add_u64 v[216:217], s[24:25], 0, v[172:173]
	s_add_i32 m0, s34, 0xc000
	ds_read_b128 v[178:181], v190
	ds_read_b128 v[182:185], v190 offset:1024
	ds_read_b128 v[192:195], v190 offset:2048
	ds_read_b128 v[196:199], v190 offset:3072
	ds_read_b128 v[200:203], v190 offset:4096
	ds_read_b128 v[204:207], v190 offset:5120
	ds_read_b128 v[208:211], v190 offset:6144
	ds_read_b128 v[212:215], v190 offset:7168
	global_load_lds_dwordx4 v[216:217], off
	v_lshl_add_u64 v[216:217], s[24:25], 0, v[174:175]
	s_add_i32 m0, s34, 0xe000
	s_nop 0
	global_load_lds_dwordx4 v[216:217], off
	s_setprio 1
	s_waitcnt vmcnt(8) lgkmcnt(0)
	s_barrier
	v_mfma_f32_16x16x128_f8f6f4 v[120:123], v[152:159], v[178:185], v[120:123]
	v_mfma_f32_16x16x128_f8f6f4 v[124:127], v[144:151], v[178:185], v[124:127]
	v_mfma_f32_16x16x128_f8f6f4 v[112:115], v[152:159], v[192:199], v[112:115]
	v_mfma_f32_16x16x128_f8f6f4 v[116:119], v[144:151], v[192:199], v[116:119]
	v_mfma_f32_16x16x128_f8f6f4 v[96:99], v[152:159], v[200:207], v[96:99]
	v_mfma_f32_16x16x128_f8f6f4 v[100:103], v[144:151], v[200:207], v[100:103]
	v_mfma_f32_16x16x128_f8f6f4 v[80:83], v[152:159], v[208:215], v[80:83]
	v_mfma_f32_16x16x128_f8f6f4 v[84:87], v[144:151], v[208:215], v[84:87]
	v_mfma_f32_16x16x128_f8f6f4 v[104:107], v[136:143], v[178:185], v[104:107]
	v_mfma_f32_16x16x128_f8f6f4 v[108:111], v[128:135], v[178:185], v[108:111]
	v_mfma_f32_16x16x128_f8f6f4 v[88:91], v[136:143], v[192:199], v[88:91]
	v_mfma_f32_16x16x128_f8f6f4 v[92:95], v[128:135], v[192:199], v[92:95]
	v_mfma_f32_16x16x128_f8f6f4 v[72:75], v[136:143], v[200:207], v[72:75]
	v_mfma_f32_16x16x128_f8f6f4 v[76:79], v[128:135], v[200:207], v[76:79]
	v_mfma_f32_16x16x128_f8f6f4 v[64:67], v[136:143], v[208:215], v[64:67]
	v_mfma_f32_16x16x128_f8f6f4 v[68:71], v[128:135], v[208:215], v[68:71]
	s_barrier
	s_setprio 0
	s_add_i32 s43, s64, s31
	v_lshl_add_u64 v[178:179], s[26:27], 0, v[162:163]
	s_mov_b32 m0, s43
	s_nop 0
	global_load_lds_dwordx4 v[178:179], off
	s_add_i32 m0, s43, 0x2000
	s_add_u32 s84, s26, 0xb0000
	v_lshl_add_u64 v[180:181], s[26:27], 0, v[166:167]
	s_addc_u32 s85, s27, 0
	s_add_i32 s43, s65, s31
	global_load_lds_dwordx4 v[180:181], off
	v_lshl_add_u64 v[182:183], s[84:85], 0, v[162:163]
	s_mov_b32 m0, s43
	v_lshl_add_u64 v[184:185], s[28:29], 0, v[164:165]
	global_load_lds_dwordx4 v[182:183], off
	v_lshl_add_u64 v[182:183], s[84:85], 0, v[166:167]
	s_add_i32 m0, s43, 0x2000
	s_nop 0
	global_load_lds_dwordx4 v[182:183], off
	v_lshl_add_u64 v[182:183], s[28:29], 0, v[160:161]
	s_mov_b32 m0, s34
	s_nop 0
	global_load_lds_dwordx4 v[182:183], off
	s_mov_b32 m0, s35
	s_nop 0
	global_load_lds_dwordx4 v[184:185], off
	ds_read_b128 v[192:195], v190 offset:16384
	ds_read_b128 v[196:199], v190 offset:17408
	ds_read_b128 v[200:203], v190 offset:18432
	ds_read_b128 v[204:207], v190 offset:19456
	ds_read_b128 v[208:211], v190 offset:20480
	ds_read_b128 v[212:215], v190 offset:21504
	ds_read_b128 v[216:219], v190 offset:22528
	ds_read_b128 v[220:223], v190 offset:23552
	s_setprio 1
	s_waitcnt vmcnt(8) lgkmcnt(0)
	s_barrier
	v_mfma_f32_16x16x128_f8f6f4 v[56:59], v[152:159], v[192:199], v[56:59]
	v_mfma_f32_16x16x128_f8f6f4 v[60:63], v[144:151], v[192:199], v[60:63]
	v_mfma_f32_16x16x128_f8f6f4 v[48:51], v[152:159], v[200:207], v[48:51]
	v_mfma_f32_16x16x128_f8f6f4 v[52:55], v[144:151], v[200:207], v[52:55]
	v_mfma_f32_16x16x128_f8f6f4 v[32:35], v[152:159], v[208:215], v[32:35]
	v_mfma_f32_16x16x128_f8f6f4 v[224:227], v[144:151], v[208:215], v[36:39]
	v_mfma_f32_16x16x128_f8f6f4 v[228:231], v[152:159], v[216:223], v[16:19]
	v_mfma_f32_16x16x128_f8f6f4 v[232:235], v[144:151], v[216:223], v[20:23]
	v_mfma_f32_16x16x128_f8f6f4 v[44:47], v[128:135], v[192:199], v[44:47]
	v_mfma_f32_16x16x128_f8f6f4 v[236:239], v[136:143], v[192:199], v[40:43]
	v_mfma_f32_16x16x128_f8f6f4 v[240:243], v[136:143], v[200:207], v[24:27]
	v_mfma_f32_16x16x128_f8f6f4 v[200:203], v[128:135], v[200:207], v[28:31]
	v_mfma_f32_16x16x128_f8f6f4 v[204:207], v[136:143], v[208:215], v[8:11]
	v_mfma_f32_16x16x128_f8f6f4 v[208:211], v[128:135], v[208:215], v[12:15]
	v_mfma_f32_16x16x128_f8f6f4 v[212:215], v[136:143], v[216:223], v[0:3]
	v_mfma_f32_16x16x128_f8f6f4 v[216:219], v[128:135], v[216:223], v[4:7]
	s_barrier
; #define PG8_STAGE(bufoff, gbase, voff) do { _Pragma("unroll") for (int _i = 0; _i < 2; ++_i) \
;         __builtin_amdgcn_global_load_lds((const unsigned*)((const char*)(gbase) + (voff)[_i]), (LAS unsigned*)(lds + (bufoff) + ldsw + _i * 8192), 16, 0, 0); } while (0)
; #define PG8_LDA(dst, b, h) do { _Pragma("unroll") for (int m = 0; m < 4; ++m) _Pragma("unroll") for (int k = 0; k < 2; ++k) dst[m][k] = *(const LAS bf16x8*)(lds + PG8_SA(b, h) + aoff + m * 2048 + k * KOFF); } while (0)
; #define PG8_LDB(dst, b, h) do { _Pragma("unroll") for (int n = 0; n < 2; ++n) _Pragma("unroll") for (int k = 0; k < 2; ++k) dst[n][k] = *(const LAS bf16x8*)(lds + PG8_SB(b, h) + boff + n * 2048 + k * KOFF); } while (0)
; #define PG8_WAIT_V(n) asm volatile("s_waitcnt vmcnt(" #n ")" ::: "memory")
; #define PG8_WAIT_L(n) asm volatile("s_waitcnt lgkmcnt(" #n ")" ::: "memory")
; #define PG8_BAR __builtin_amdgcn_s_barrier()
; #define PG8_SCHED __builtin_amdgcn_sched_barrier(0)
; template <class Epi, bool ALIGN_EPI = true, bool FP8 = false>
; __device__ __forceinline__ void gemm_phase(LAS unsigned char* lds, const Gemm g, const StaticOrder& S, const Epi& E, const int wid) {
;     ...
;             PG8_LDB(B0, 1, 0); PG8_LDB(B1, 1, 1); PG8_SCHED; PG8_LDA(At, 1, 0); PG8_STAGE(PG8_SA(0, 1), a2 + hstep, voffA);
;             PG8_WAIT_V(8); PG8_WAIT_L(0); PG8_BAR; PG8_MMA(0, 0, At, B0); PG8_MMA(0, 1, At, B1); PG8_BAR; PG8_SCHED;
;             PG8_LDA(At, 1, 1); PG8_STAGE(PG8_SB(1, 0), b3, voffB); PG8_STAGE(PG8_SB(1, 1), b3 + hstep, voffB); PG8_STAGE(PG8_SA(1, 0), a3, voffA);
;             PG8_WAIT_V(8); PG8_WAIT_L(0); PG8_BAR; PG8_MMA(1, 0, At, B0); PG8_MMA(1, 1, At, B1); PG8_BAR; PG8_SCHED;
;         }
	s_setprio 0
	s_add_i32 s43, 0, 0x18000
	s_add_i32 s54, 0, 0x1c000
	s_nop 0
	v_add_u32_e32 v12, s43, v187
	v_add_u32_e32 v16, s54, v187
	ds_read_b128 v[0:3], v12
	ds_read_b128 v[4:7], v12 offset:1024
	ds_read_b128 v[8:11], v12 offset:2048
	ds_read_b128 v[12:15], v12 offset:3072
	ds_read_b128 v[128:131], v16
	ds_read_b128 v[132:135], v16 offset:1024
	ds_read_b128 v[136:139], v16 offset:2048
	ds_read_b128 v[140:143], v16 offset:3072
	s_add_u32 s28, s28, 0xb0000
	s_addc_u32 s29, s29, 0
	s_mov_b32 m0, s36
	v_lshl_add_u64 v[152:153], s[28:29], 0, v[160:161]
	ds_read_b128 v[16:19], v190 offset:32768
	ds_read_b128 v[20:23], v190 offset:33792
	ds_read_b128 v[24:27], v190 offset:34816
	ds_read_b128 v[28:31], v190 offset:35840
	ds_read_b128 v[36:39], v190 offset:36864
	ds_read_b128 v[40:43], v190 offset:37888
	ds_read_b128 v[144:147], v190 offset:38912
	ds_read_b128 v[148:151], v190 offset:39936
	global_load_lds_dwordx4 v[152:153], off
	v_lshl_add_u64 v[152:153], s[28:29], 0, v[164:165]
	s_mov_b32 m0, s37
	s_nop 0
	global_load_lds_dwordx4 v[152:153], off
	s_setprio 1
	s_waitcnt vmcnt(8) lgkmcnt(0)
	s_barrier
	v_mfma_f32_16x16x128_f8f6f4 v[120:123], v[0:7], v[16:23], v[120:123]
	v_mfma_f32_16x16x128_f8f6f4 v[124:127], v[8:15], v[16:23], v[124:127]
	v_mfma_f32_16x16x128_f8f6f4 v[112:115], v[0:7], v[24:31], v[112:115]
	v_mfma_f32_16x16x128_f8f6f4 v[116:119], v[8:15], v[24:31], v[116:119]
	v_mfma_f32_16x16x128_f8f6f4 v[96:99], v[0:7], v[36:43], v[96:99]
	v_mfma_f32_16x16x128_f8f6f4 v[100:103], v[8:15], v[36:43], v[100:103]
	v_mfma_f32_16x16x128_f8f6f4 v[80:83], v[0:7], v[144:151], v[80:83]
	v_mfma_f32_16x16x128_f8f6f4 v[84:87], v[8:15], v[144:151], v[84:87]
	v_mfma_f32_16x16x128_f8f6f4 v[104:107], v[128:135], v[16:23], v[104:107]
	v_mfma_f32_16x16x128_f8f6f4 v[108:111], v[136:143], v[16:23], v[108:111]
	v_mfma_f32_16x16x128_f8f6f4 v[88:91], v[128:135], v[24:31], v[88:91]
	v_mfma_f32_16x16x128_f8f6f4 v[92:95], v[136:143], v[24:31], v[92:95]
	v_mfma_f32_16x16x128_f8f6f4 v[72:75], v[128:135], v[36:43], v[72:75]
	v_mfma_f32_16x16x128_f8f6f4 v[76:79], v[136:143], v[36:43], v[76:79]
	v_mfma_f32_16x16x128_f8f6f4 v[64:67], v[128:135], v[144:151], v[64:67]
	v_mfma_f32_16x16x128_f8f6f4 v[68:71], v[136:143], v[144:151], v[68:71]
	s_barrier
	s_setprio 0
	s_add_i32 s28, s43, s31
	v_lshl_add_u64 v[16:17], v[178:179], 0, s[14:15]
	s_mov_b32 m0, s28
	s_nop 0
	global_load_lds_dwordx4 v[16:17], off
	s_add_i32 m0, s28, 0x2000
	s_add_u32 s26, s26, 0xb0080
	v_lshl_add_u64 v[16:17], v[180:181], 0, s[14:15]
	s_addc_u32 s27, s27, 0
	s_add_i32 s28, s54, s31
	global_load_lds_dwordx4 v[16:17], off
	v_lshl_add_u64 v[16:17], s[26:27], 0, v[162:163]
	s_mov_b32 m0, s28
	s_nop 0
	global_load_lds_dwordx4 v[16:17], off
	v_lshl_add_u64 v[16:17], s[26:27], 0, v[166:167]
	s_add_i32 m0, s28, 0x2000
	s_nop 0
	global_load_lds_dwordx4 v[16:17], off
	v_lshl_add_u64 v[16:17], v[182:183], 0, s[14:15]
	s_mov_b32 m0, s52
	s_nop 0
	global_load_lds_dwordx4 v[16:17], off
	v_lshl_add_u64 v[16:17], v[184:185], 0, s[14:15]
	s_mov_b32 m0, s53
	s_nop 0
	global_load_lds_dwordx4 v[16:17], off
	ds_read_b128 v[24:27], v190 offset:49152
	ds_read_b128 v[28:31], v190 offset:50176
	ds_read_b128 v[144:147], v190 offset:51200
	ds_read_b128 v[148:151], v190 offset:52224
	ds_read_b128 v[152:155], v190 offset:53248
	ds_read_b128 v[156:159], v190 offset:54272
	ds_read_b128 v[192:195], v190 offset:55296
	ds_read_b128 v[196:199], v190 offset:56320
	s_setprio 1
	s_waitcnt vmcnt(8) lgkmcnt(0)
	s_barrier
	v_mfma_f32_16x16x128_f8f6f4 v[56:59], v[0:7], v[24:31], v[56:59]
	v_mfma_f32_16x16x128_f8f6f4 v[60:63], v[8:15], v[24:31], v[60:63]
	v_mfma_f32_16x16x128_f8f6f4 v[48:51], v[0:7], v[144:151], v[48:51]
	v_mfma_f32_16x16x128_f8f6f4 v[52:55], v[8:15], v[144:151], v[52:55]
	v_mfma_f32_16x16x128_f8f6f4 v[32:35], v[0:7], v[152:159], v[32:35]
	v_mfma_f32_16x16x128_f8f6f4 v[36:39], v[8:15], v[152:159], v[224:227]
	v_mfma_f32_16x16x128_f8f6f4 v[16:19], v[0:7], v[192:199], v[228:231]
	v_mfma_f32_16x16x128_f8f6f4 v[20:23], v[8:15], v[192:199], v[232:235]
	v_mfma_f32_16x16x128_f8f6f4 v[40:43], v[128:135], v[24:31], v[236:239]
	v_mfma_f32_16x16x128_f8f6f4 v[44:47], v[136:143], v[24:31], v[44:47]
	v_mfma_f32_16x16x128_f8f6f4 v[24:27], v[128:135], v[144:151], v[240:243]
	v_mfma_f32_16x16x128_f8f6f4 v[28:31], v[136:143], v[144:151], v[200:203]
	v_mfma_f32_16x16x128_f8f6f4 v[8:11], v[128:135], v[152:159], v[204:207]
	v_mfma_f32_16x16x128_f8f6f4 v[12:15], v[136:143], v[152:159], v[208:211]
	v_mfma_f32_16x16x128_f8f6f4 v[0:3], v[128:135], v[192:199], v[212:215]
	v_mfma_f32_16x16x128_f8f6f4 v[4:7], v[136:143], v[192:199], v[216:219]
	s_barrier
	s_setprio 0
	s_add_u32 s24, s24, 0x100
	s_addc_u32 s25, s25, 0
	s_add_u32 s82, s82, 0x100
	s_addc_u32 s83, s83, 0
	s_cmp_ge_u32 s42, s80
	s_mov_b32 s26, s42
	s_cbranch_scc0 .LBB0_2536
	s_and_b64 vcc, exec, s[16:17]
	s_cbranch_vccz .LBB0_2539
	s_barrier
